# LDS fragment-read base addresses hoisted out of the four FFN K-loops (no VALU left in those loops)
# speedup vs baseline: 1.0203x; 1.0031x over previous
.LBB0_401:
	v_mov_b64_e32 v[0:1], 0x580
	s_ashr_i32 s9, s8, 31
	v_cmp_lt_i64_e32 vcc, s[12:13], v[0:1]
	s_lshl_b64 s[12:13], s[8:9], 19
	v_readlane_b32 s14, v254, 33
	v_readlane_b32 s15, v254, 34
	s_add_u32 s12, s14, s12
	s_addc_u32 s13, s15, s13
	s_and_b64 s[14:15], vcc, exec
	s_cselect_b32 s1, s13, s21
	s_cselect_b32 s9, s12, s20
	s_ashr_i32 s11, s10, 31
	s_lshl_b64 s[14:15], s[10:11], 19
	s_add_u32 s14, s26, s14
	s_addc_u32 s15, s27, s15
	s_and_b64 s[22:23], vcc, exec
	s_cselect_b32 s11, s15, s19
	s_cselect_b32 s33, s14, s18
	s_add_u32 s38, s18, 0x100
	s_addc_u32 s39, s19, 0
	s_add_u32 s18, s20, 0x40080
	v_mov_b32_e32 v0, 0
	s_addc_u32 s19, s21, 0
	s_mov_b32 s40, -2
	v_mov_b32_e32 v1, v0
	v_mov_b32_e32 v2, v0
	v_mov_b32_e32 v3, v0
	v_mov_b32_e32 v8, v0
	v_mov_b32_e32 v9, v0
	v_mov_b32_e32 v10, v0
	v_mov_b32_e32 v11, v0
	v_mov_b32_e32 v16, v0
	v_mov_b32_e32 v17, v0
	v_mov_b32_e32 v18, v0
	v_mov_b32_e32 v19, v0
	v_mov_b32_e32 v24, v0
	v_mov_b32_e32 v25, v0
	v_mov_b32_e32 v26, v0
	v_mov_b32_e32 v27, v0
	v_mov_b32_e32 v32, v0
	v_mov_b32_e32 v33, v0
	v_mov_b32_e32 v34, v0
	v_mov_b32_e32 v35, v0
	v_mov_b32_e32 v40, v0
	v_mov_b32_e32 v41, v0
	v_mov_b32_e32 v42, v0
	v_mov_b32_e32 v43, v0
	v_mov_b32_e32 v48, v0
	v_mov_b32_e32 v49, v0
	v_mov_b32_e32 v50, v0
	v_mov_b32_e32 v51, v0
	v_mov_b32_e32 v56, v0
	v_mov_b32_e32 v57, v0
	v_mov_b32_e32 v58, v0
	v_mov_b32_e32 v59, v0
	v_mov_b32_e32 v4, v0
	v_mov_b32_e32 v5, v0
	v_mov_b32_e32 v6, v0
	v_mov_b32_e32 v7, v0
	v_mov_b32_e32 v12, v0
	v_mov_b32_e32 v13, v0
	v_mov_b32_e32 v14, v0
	v_mov_b32_e32 v15, v0
	v_mov_b32_e32 v20, v0
	v_mov_b32_e32 v21, v0
	v_mov_b32_e32 v22, v0
	v_mov_b32_e32 v23, v0
	v_mov_b32_e32 v28, v0
	v_mov_b32_e32 v29, v0
	v_mov_b32_e32 v30, v0
	v_mov_b32_e32 v31, v0
	v_mov_b32_e32 v36, v0
	v_mov_b32_e32 v37, v0
	v_mov_b32_e32 v38, v0
	v_mov_b32_e32 v39, v0
	v_mov_b32_e32 v44, v0
	v_mov_b32_e32 v45, v0
	v_mov_b32_e32 v46, v0
	v_mov_b32_e32 v47, v0
	v_mov_b32_e32 v52, v0
	v_mov_b32_e32 v53, v0
	v_mov_b32_e32 v54, v0
	v_mov_b32_e32 v55, v0
	v_mov_b32_e32 v60, v0
	v_mov_b32_e32 v61, v0
	v_mov_b32_e32 v62, v0
	v_mov_b32_e32 v63, v0
	s_waitcnt vmcnt(0)
	v_mov_b32_e32 v64, v0
	v_mov_b32_e32 v65, v0
	v_mov_b32_e32 v66, v0
	v_mov_b32_e32 v67, v0
	v_mov_b32_e32 v72, v0
	v_mov_b32_e32 v73, v0
	v_mov_b32_e32 v74, v0
	v_mov_b32_e32 v75, v0
	v_mov_b32_e32 v80, v0
	v_mov_b32_e32 v81, v0
	v_mov_b32_e32 v82, v0
	v_mov_b32_e32 v83, v0
	v_mov_b32_e32 v88, v0
	v_mov_b32_e32 v89, v0
	v_mov_b32_e32 v90, v0
	v_mov_b32_e32 v91, v0
	v_mov_b32_e32 v96, v0
	v_mov_b32_e32 v97, v0
	v_mov_b32_e32 v98, v0
	v_mov_b32_e32 v99, v0
	v_mov_b32_e32 v104, v0
	v_mov_b32_e32 v105, v0
	v_mov_b32_e32 v106, v0
	v_mov_b32_e32 v107, v0
	v_mov_b32_e32 v112, v0
	v_mov_b32_e32 v113, v0
	v_mov_b32_e32 v114, v0
	v_mov_b32_e32 v115, v0
	v_mov_b32_e32 v120, v0
	v_mov_b32_e32 v121, v0
	v_mov_b32_e32 v122, v0
	v_mov_b32_e32 v123, v0
	v_mov_b32_e32 v68, v0
	v_mov_b32_e32 v69, v0
	v_mov_b32_e32 v70, v0
	v_mov_b32_e32 v71, v0
	v_mov_b32_e32 v76, v0
	v_mov_b32_e32 v77, v0
	v_mov_b32_e32 v78, v0
	v_mov_b32_e32 v79, v0
	v_mov_b32_e32 v84, v0
	v_mov_b32_e32 v85, v0
	v_mov_b32_e32 v86, v0
	v_mov_b32_e32 v87, v0
	v_mov_b32_e32 v92, v0
	v_mov_b32_e32 v93, v0
	v_mov_b32_e32 v94, v0
	v_mov_b32_e32 v95, v0
	v_mov_b32_e32 v100, v0
	v_mov_b32_e32 v101, v0
	v_mov_b32_e32 v102, v0
	v_mov_b32_e32 v103, v0
	v_mov_b32_e32 v108, v0
	v_mov_b32_e32 v109, v0
	v_mov_b32_e32 v110, v0
	v_mov_b32_e32 v111, v0
	v_mov_b32_e32 v116, v0
	v_mov_b32_e32 v117, v0
	v_mov_b32_e32 v118, v0
	v_mov_b32_e32 v119, v0
	v_mov_b32_e32 v124, v0
	v_mov_b32_e32 v125, v0
	v_mov_b32_e32 v126, v0
	v_mov_b32_e32 v127, v0
	v_add_u32_e32 v218, 0x10000, v145
	v_add_u32_e32 v219, 0x14000, v145
	v_add_u32_e32 v220, 0x18000, v145
	v_add_u32_e32 v221, 0x1c000, v145
.LBB0_402:
	s_add_u32 s20, s18, 0xfffc0080
	s_addc_u32 s21, s19, -1
	s_add_i32 s41, 0, 0x10000
	ds_read_b128 v[138:141], v218
	ds_read_b128 v[148:151], v218 offset:1024
	ds_read_b128 v[152:155], v218 offset:2048
	ds_read_b128 v[156:159], v218 offset:3072
	s_cmp_eq_u32 s40, 12
	s_cselect_b32 s23, s1, s21
	s_cselect_b32 s22, s9, s20
	s_cselect_b32 s21, s11, s39
	s_cselect_b32 s20, s33, s38
	s_add_i32 m0, s17, 0xc000
	ds_read_b128 v[160:163], v146
	ds_read_b128 v[164:167], v146 offset:1024
	ds_read_b128 v[168:171], v146 offset:2048
	ds_read_b128 v[172:175], v146 offset:3072
	ds_read_b128 v[176:179], v146 offset:4096
	ds_read_b128 v[180:183], v146 offset:5120
	ds_read_b128 v[184:187], v146 offset:6144
	ds_read_b128 v[188:191], v146 offset:7168
	global_load_lds_dwordx4 v136, s[18:19]
	s_add_i32 m0, s17, 0xe000
	s_nop 0
	global_load_lds_dwordx4 v134, s[18:19]
	s_waitcnt lgkmcnt(8)
	s_barrier
	s_waitcnt lgkmcnt(0)
	s_setprio 1
	s_waitcnt lgkmcnt(0)
	v_mfma_f32_16x16x32_bf16 v[124:127], v[138:141], v[160:163], v[124:127]
	v_mfma_f32_16x16x32_bf16 v[116:119], v[152:155], v[160:163], v[116:119]
	v_mfma_f32_16x16x32_bf16 v[108:111], v[138:141], v[168:171], v[108:111]
	v_mfma_f32_16x16x32_bf16 v[100:103], v[152:155], v[168:171], v[100:103]
	v_mfma_f32_16x16x32_bf16 v[92:95], v[138:141], v[176:179], v[92:95]
	v_mfma_f32_16x16x32_bf16 v[84:87], v[152:155], v[176:179], v[84:87]
	v_mfma_f32_16x16x32_bf16 v[76:79], v[138:141], v[184:187], v[76:79]
	v_mfma_f32_16x16x32_bf16 v[68:71], v[152:155], v[184:187], v[68:71]
	v_mfma_f32_16x16x32_bf16 v[124:127], v[148:151], v[164:167], v[124:127]
	v_mfma_f32_16x16x32_bf16 v[116:119], v[156:159], v[164:167], v[116:119]
	v_mfma_f32_16x16x32_bf16 v[108:111], v[148:151], v[172:175], v[108:111]
	v_mfma_f32_16x16x32_bf16 v[100:103], v[156:159], v[172:175], v[100:103]
	v_mfma_f32_16x16x32_bf16 v[92:95], v[148:151], v[180:183], v[92:95]
	v_mfma_f32_16x16x32_bf16 v[84:87], v[156:159], v[180:183], v[84:87]
	v_mfma_f32_16x16x32_bf16 v[76:79], v[148:151], v[188:191], v[76:79]
	v_mfma_f32_16x16x32_bf16 v[68:71], v[156:159], v[188:191], v[68:71]
	s_setprio 0
	s_barrier
	s_add_i32 s44, 0, 0x14000
	s_add_i32 s41, s41, s28
	ds_read_b128 v[198:201], v219
	ds_read_b128 v[206:209], v219 offset:1024
	ds_read_b128 v[210:213], v219 offset:2048
	ds_read_b128 v[214:217], v219 offset:3072
	s_mov_b32 m0, s41
	s_nop 0
	global_load_lds_dwordx4 v192, s[20:21]
	s_add_i32 m0, s41, 0x2000
	s_nop 0
	global_load_lds_dwordx4 v128, s[20:21]
	s_barrier
	s_waitcnt lgkmcnt(0)
	s_setprio 1
	s_waitcnt lgkmcnt(0)
	v_mfma_f32_16x16x32_bf16 v[120:123], v[198:201], v[160:163], v[120:123]
	v_mfma_f32_16x16x32_bf16 v[112:115], v[210:213], v[160:163], v[112:115]
	v_mfma_f32_16x16x32_bf16 v[104:107], v[198:201], v[168:171], v[104:107]
	v_mfma_f32_16x16x32_bf16 v[96:99], v[210:213], v[168:171], v[96:99]
	v_mfma_f32_16x16x32_bf16 v[88:91], v[198:201], v[176:179], v[88:91]
	v_mfma_f32_16x16x32_bf16 v[80:83], v[210:213], v[176:179], v[80:83]
	v_mfma_f32_16x16x32_bf16 v[72:75], v[198:201], v[184:187], v[72:75]
	v_mfma_f32_16x16x32_bf16 v[64:67], v[210:213], v[184:187], v[64:67]
	v_mfma_f32_16x16x32_bf16 v[120:123], v[206:209], v[164:167], v[120:123]
	v_mfma_f32_16x16x32_bf16 v[112:115], v[214:217], v[164:167], v[112:115]
	v_mfma_f32_16x16x32_bf16 v[104:107], v[206:209], v[172:175], v[104:107]
	v_mfma_f32_16x16x32_bf16 v[96:99], v[214:217], v[172:175], v[96:99]
	v_mfma_f32_16x16x32_bf16 v[88:91], v[206:209], v[180:183], v[88:91]
	v_mfma_f32_16x16x32_bf16 v[80:83], v[214:217], v[180:183], v[80:83]
	v_mfma_f32_16x16x32_bf16 v[72:75], v[206:209], v[188:191], v[72:75]
	v_mfma_f32_16x16x32_bf16 v[64:67], v[214:217], v[188:191], v[64:67]
	s_setprio 0
	s_mov_b32 m0, s17
	s_add_u32 vcc_lo, s22, 0x80
	s_addc_u32 vcc_hi, s23, 0
	s_barrier
	ds_read_b128 v[160:163], v146 offset:16384
	ds_read_b128 v[164:167], v146 offset:17408
	ds_read_b128 v[168:171], v146 offset:18432
	ds_read_b128 v[172:175], v146 offset:19456
	ds_read_b128 v[176:179], v146 offset:20480
	ds_read_b128 v[180:183], v146 offset:21504
	ds_read_b128 v[184:187], v146 offset:22528
	ds_read_b128 v[188:191], v146 offset:23552
	global_load_lds_dwordx4 v132, s[22:23]
	s_mov_b32 m0, s29
	s_nop 0
	global_load_lds_dwordx4 v130, s[22:23]
	s_barrier
	s_waitcnt lgkmcnt(0)
	s_setprio 1
	s_waitcnt lgkmcnt(0)
	v_mfma_f32_16x16x32_bf16 v[60:63], v[138:141], v[160:163], v[60:63]
	v_mfma_f32_16x16x32_bf16 v[52:55], v[152:155], v[160:163], v[52:55]
	v_mfma_f32_16x16x32_bf16 v[44:47], v[138:141], v[168:171], v[44:47]
	v_mfma_f32_16x16x32_bf16 v[36:39], v[152:155], v[168:171], v[36:39]
	v_mfma_f32_16x16x32_bf16 v[28:31], v[138:141], v[176:179], v[28:31]
	v_mfma_f32_16x16x32_bf16 v[20:23], v[152:155], v[176:179], v[20:23]
	v_mfma_f32_16x16x32_bf16 v[12:15], v[138:141], v[184:187], v[12:15]
	v_mfma_f32_16x16x32_bf16 v[4:7], v[152:155], v[184:187], v[4:7]
	v_mfma_f32_16x16x32_bf16 v[60:63], v[148:151], v[164:167], v[60:63]
	v_mfma_f32_16x16x32_bf16 v[52:55], v[156:159], v[164:167], v[52:55]
	v_mfma_f32_16x16x32_bf16 v[44:47], v[148:151], v[172:175], v[44:47]
	v_mfma_f32_16x16x32_bf16 v[36:39], v[156:159], v[172:175], v[36:39]
	v_mfma_f32_16x16x32_bf16 v[28:31], v[148:151], v[180:183], v[28:31]
	v_mfma_f32_16x16x32_bf16 v[20:23], v[156:159], v[180:183], v[20:23]
	v_mfma_f32_16x16x32_bf16 v[12:15], v[148:151], v[188:191], v[12:15]
	v_mfma_f32_16x16x32_bf16 v[4:7], v[156:159], v[188:191], v[4:7]
	s_setprio 0
	s_barrier
	s_add_u32 s42, s20, 0x40000
	s_addc_u32 s43, s21, 0
	s_add_i32 s41, s44, s28
	s_mov_b32 m0, s41
	s_nop 0
	global_load_lds_dwordx4 v192, s[42:43]
	s_add_i32 m0, s41, 0x2000
	s_nop 0
	global_load_lds_dwordx4 v128, s[42:43]
	s_waitcnt vmcnt(6)
	s_barrier
	s_setprio 1
	v_mfma_f32_16x16x32_bf16 v[56:59], v[198:201], v[160:163], v[56:59]
	v_mfma_f32_16x16x32_bf16 v[48:51], v[210:213], v[160:163], v[48:51]
	v_mfma_f32_16x16x32_bf16 v[40:43], v[198:201], v[168:171], v[40:43]
	v_mfma_f32_16x16x32_bf16 v[32:35], v[210:213], v[168:171], v[32:35]
	v_mfma_f32_16x16x32_bf16 v[24:27], v[198:201], v[176:179], v[24:27]
	v_mfma_f32_16x16x32_bf16 v[16:19], v[210:213], v[176:179], v[16:19]
	v_mfma_f32_16x16x32_bf16 v[8:11], v[198:201], v[184:187], v[8:11]
	v_mfma_f32_16x16x32_bf16 v[0:3], v[210:213], v[184:187], v[0:3]
	v_mfma_f32_16x16x32_bf16 v[56:59], v[206:209], v[164:167], v[56:59]
	v_mfma_f32_16x16x32_bf16 v[48:51], v[214:217], v[164:167], v[48:51]
	v_mfma_f32_16x16x32_bf16 v[40:43], v[206:209], v[172:175], v[40:43]
	v_mfma_f32_16x16x32_bf16 v[32:35], v[214:217], v[172:175], v[32:35]
	v_mfma_f32_16x16x32_bf16 v[24:27], v[206:209], v[180:183], v[24:27]
	v_mfma_f32_16x16x32_bf16 v[16:19], v[214:217], v[180:183], v[16:19]
	v_mfma_f32_16x16x32_bf16 v[8:11], v[206:209], v[188:191], v[8:11]
	v_mfma_f32_16x16x32_bf16 v[0:3], v[214:217], v[188:191], v[0:3]
	s_setprio 0
	s_add_i32 s41, 0, 0x18000
	s_barrier
	ds_read_b128 v[138:141], v220
	ds_read_b128 v[148:151], v220 offset:1024
	ds_read_b128 v[152:155], v220 offset:2048
	ds_read_b128 v[156:159], v220 offset:3072
	s_add_u32 s22, s22, 0x40000
	s_addc_u32 s23, s23, 0
	s_mov_b32 m0, s30
	ds_read_b128 v[160:163], v146 offset:32768
	ds_read_b128 v[164:167], v146 offset:33792
	ds_read_b128 v[168:171], v146 offset:34816
	ds_read_b128 v[172:175], v146 offset:35840
	ds_read_b128 v[176:179], v146 offset:36864
	ds_read_b128 v[180:183], v146 offset:37888
	ds_read_b128 v[184:187], v146 offset:38912
	ds_read_b128 v[188:191], v146 offset:39936
	global_load_lds_dwordx4 v132, s[22:23]
	s_mov_b32 m0, s31
	s_nop 0
	global_load_lds_dwordx4 v130, s[22:23]
	s_waitcnt lgkmcnt(8)
	s_barrier
	s_waitcnt lgkmcnt(0)
	s_setprio 1
	s_waitcnt lgkmcnt(0)
	v_mfma_f32_16x16x32_bf16 v[124:127], v[138:141], v[160:163], v[124:127]
	v_mfma_f32_16x16x32_bf16 v[116:119], v[152:155], v[160:163], v[116:119]
	v_mfma_f32_16x16x32_bf16 v[108:111], v[138:141], v[168:171], v[108:111]
	v_mfma_f32_16x16x32_bf16 v[100:103], v[152:155], v[168:171], v[100:103]
	v_mfma_f32_16x16x32_bf16 v[92:95], v[138:141], v[176:179], v[92:95]
	v_mfma_f32_16x16x32_bf16 v[84:87], v[152:155], v[176:179], v[84:87]
	v_mfma_f32_16x16x32_bf16 v[76:79], v[138:141], v[184:187], v[76:79]
	v_mfma_f32_16x16x32_bf16 v[68:71], v[152:155], v[184:187], v[68:71]
	v_mfma_f32_16x16x32_bf16 v[124:127], v[148:151], v[164:167], v[124:127]
	v_mfma_f32_16x16x32_bf16 v[116:119], v[156:159], v[164:167], v[116:119]
	v_mfma_f32_16x16x32_bf16 v[108:111], v[148:151], v[172:175], v[108:111]
	v_mfma_f32_16x16x32_bf16 v[100:103], v[156:159], v[172:175], v[100:103]
	v_mfma_f32_16x16x32_bf16 v[92:95], v[148:151], v[180:183], v[92:95]
	v_mfma_f32_16x16x32_bf16 v[84:87], v[156:159], v[180:183], v[84:87]
	v_mfma_f32_16x16x32_bf16 v[76:79], v[148:151], v[188:191], v[76:79]
	v_mfma_f32_16x16x32_bf16 v[68:71], v[156:159], v[188:191], v[68:71]
	s_setprio 0
	s_barrier
	s_add_i32 s22, 0, 0x1c000
	s_add_i32 s23, s41, s28
	s_add_u32 s100, s20, 0x80
	s_addc_u32 s101, s21, 0
	s_mov_b32 m0, s23
	ds_read_b128 v[198:201], v221
	ds_read_b128 v[206:209], v221 offset:1024
	ds_read_b128 v[210:213], v221 offset:2048
	ds_read_b128 v[214:217], v221 offset:3072
	global_load_lds_dwordx4 v192, s[100:101]
	s_add_i32 m0, s23, 0x2000
	s_nop 0
	global_load_lds_dwordx4 v128, s[100:101]
	s_barrier
	s_waitcnt lgkmcnt(0)
	s_setprio 1
	s_waitcnt lgkmcnt(0)
	v_mfma_f32_16x16x32_bf16 v[120:123], v[198:201], v[160:163], v[120:123]
	v_mfma_f32_16x16x32_bf16 v[112:115], v[210:213], v[160:163], v[112:115]
	v_mfma_f32_16x16x32_bf16 v[104:107], v[198:201], v[168:171], v[104:107]
	v_mfma_f32_16x16x32_bf16 v[96:99], v[210:213], v[168:171], v[96:99]
	v_mfma_f32_16x16x32_bf16 v[88:91], v[198:201], v[176:179], v[88:91]
	v_mfma_f32_16x16x32_bf16 v[80:83], v[210:213], v[176:179], v[80:83]
	v_mfma_f32_16x16x32_bf16 v[72:75], v[198:201], v[184:187], v[72:75]
	v_mfma_f32_16x16x32_bf16 v[64:67], v[210:213], v[184:187], v[64:67]
	v_mfma_f32_16x16x32_bf16 v[120:123], v[206:209], v[164:167], v[120:123]
	v_mfma_f32_16x16x32_bf16 v[112:115], v[214:217], v[164:167], v[112:115]
	v_mfma_f32_16x16x32_bf16 v[104:107], v[206:209], v[172:175], v[104:107]
	v_mfma_f32_16x16x32_bf16 v[96:99], v[214:217], v[172:175], v[96:99]
	v_mfma_f32_16x16x32_bf16 v[88:91], v[206:209], v[180:183], v[88:91]
	v_mfma_f32_16x16x32_bf16 v[80:83], v[214:217], v[180:183], v[80:83]
	v_mfma_f32_16x16x32_bf16 v[72:75], v[206:209], v[188:191], v[72:75]
	v_mfma_f32_16x16x32_bf16 v[64:67], v[214:217], v[188:191], v[64:67]
	s_setprio 0
	s_mov_b32 m0, s34
	s_barrier
	ds_read_b128 v[160:163], v146 offset:49152
	ds_read_b128 v[164:167], v146 offset:50176
	ds_read_b128 v[168:171], v146 offset:51200
	ds_read_b128 v[172:175], v146 offset:52224
	ds_read_b128 v[176:179], v146 offset:53248
	ds_read_b128 v[180:183], v146 offset:54272
	ds_read_b128 v[184:187], v146 offset:55296
	ds_read_b128 v[188:191], v146 offset:56320
	global_load_lds_dwordx4 v132, vcc
	s_mov_b32 m0, s35
	s_nop 0
	global_load_lds_dwordx4 v130, vcc
	s_barrier
	s_waitcnt lgkmcnt(0)
	s_setprio 1
	s_waitcnt lgkmcnt(0)
	v_mfma_f32_16x16x32_bf16 v[60:63], v[138:141], v[160:163], v[60:63]
	v_mfma_f32_16x16x32_bf16 v[52:55], v[152:155], v[160:163], v[52:55]
	v_mfma_f32_16x16x32_bf16 v[44:47], v[138:141], v[168:171], v[44:47]
	v_mfma_f32_16x16x32_bf16 v[36:39], v[152:155], v[168:171], v[36:39]
	v_mfma_f32_16x16x32_bf16 v[28:31], v[138:141], v[176:179], v[28:31]
	v_mfma_f32_16x16x32_bf16 v[20:23], v[152:155], v[176:179], v[20:23]
	v_mfma_f32_16x16x32_bf16 v[12:15], v[138:141], v[184:187], v[12:15]
	v_mfma_f32_16x16x32_bf16 v[4:7], v[152:155], v[184:187], v[4:7]
	v_mfma_f32_16x16x32_bf16 v[60:63], v[148:151], v[164:167], v[60:63]
	v_mfma_f32_16x16x32_bf16 v[52:55], v[156:159], v[164:167], v[52:55]
	v_mfma_f32_16x16x32_bf16 v[44:47], v[148:151], v[172:175], v[44:47]
	v_mfma_f32_16x16x32_bf16 v[36:39], v[156:159], v[172:175], v[36:39]
	v_mfma_f32_16x16x32_bf16 v[28:31], v[148:151], v[180:183], v[28:31]
	v_mfma_f32_16x16x32_bf16 v[20:23], v[156:159], v[180:183], v[20:23]
	v_mfma_f32_16x16x32_bf16 v[12:15], v[148:151], v[188:191], v[12:15]
	v_mfma_f32_16x16x32_bf16 v[4:7], v[156:159], v[188:191], v[4:7]
	s_setprio 0
	s_barrier
	s_add_u32 s20, s20, 0x40080
	s_addc_u32 s21, s21, 0
	s_add_i32 s22, s22, s28
	s_mov_b32 m0, s22
	s_nop 0
	global_load_lds_dwordx4 v192, s[20:21]
	s_add_i32 m0, s22, 0x2000
	s_nop 0
	global_load_lds_dwordx4 v128, s[20:21]
	s_waitcnt vmcnt(6)
	s_barrier
	s_setprio 1
	v_mfma_f32_16x16x32_bf16 v[56:59], v[198:201], v[160:163], v[56:59]
	v_mfma_f32_16x16x32_bf16 v[48:51], v[210:213], v[160:163], v[48:51]
	v_mfma_f32_16x16x32_bf16 v[40:43], v[198:201], v[168:171], v[40:43]
	v_mfma_f32_16x16x32_bf16 v[32:35], v[210:213], v[168:171], v[32:35]
	v_mfma_f32_16x16x32_bf16 v[24:27], v[198:201], v[176:179], v[24:27]
	v_mfma_f32_16x16x32_bf16 v[16:19], v[210:213], v[176:179], v[16:19]
	v_mfma_f32_16x16x32_bf16 v[8:11], v[198:201], v[184:187], v[8:11]
	v_mfma_f32_16x16x32_bf16 v[0:3], v[210:213], v[184:187], v[0:3]
	v_mfma_f32_16x16x32_bf16 v[56:59], v[206:209], v[164:167], v[56:59]
	v_mfma_f32_16x16x32_bf16 v[48:51], v[214:217], v[164:167], v[48:51]
	v_mfma_f32_16x16x32_bf16 v[40:43], v[206:209], v[172:175], v[40:43]
	v_mfma_f32_16x16x32_bf16 v[32:35], v[214:217], v[172:175], v[32:35]
	v_mfma_f32_16x16x32_bf16 v[24:27], v[206:209], v[180:183], v[24:27]
	v_mfma_f32_16x16x32_bf16 v[16:19], v[214:217], v[180:183], v[16:19]
	v_mfma_f32_16x16x32_bf16 v[8:11], v[206:209], v[188:191], v[8:11]
	v_mfma_f32_16x16x32_bf16 v[0:3], v[214:217], v[188:191], v[0:3]
	s_setprio 0
	s_add_i32 s40, s40, 2
	s_add_u32 s38, s38, 0x100
	s_addc_u32 s39, s39, 0
	s_add_u32 s18, s18, 0x100
	s_addc_u32 s19, s19, 0
	s_cmp_gt_u32 s40, 13
	s_barrier
	s_cbranch_scc0 .LBB0_402
	v_mov_b32_e32 v139, v252
	s_lshl_b32 s9, s16, 8
	v_readfirstlane_b32 s1, v139
	s_ashr_i32 s11, s1, 2
	s_andn2_b32 s11, s11, 63
	s_lshr_b32 s1, s1, 1
	s_add_i32 s11, s11, s9
	s_lshl_b32 s0, s0, 7
	s_and_b32 s1, s1, 0x60
	v_and_or_b32 v138, v139, 15, s11
	s_or_b32 s0, s1, s0
	v_lshrrev_b32_e32 v139, 1, v139
	v_and_or_b32 v142, v139, 24, s0
	v_ashrrev_i32_e32 v139, 31, v138
	v_lshl_add_u64 v[140:141], v[138:139], 2, s[6:7]
	v_pk_mul_f32 v[120:121], v[124:125], v[120:121]
	v_pk_mul_f32 v[122:123], v[126:127], v[122:123]
	v_pk_mul_f32 v[112:113], v[116:117], v[112:113]
	v_pk_mul_f32 v[114:115], v[118:119], v[114:115]
	v_ashrrev_i32_e32 v143, 31, v142
	s_movk_i32 s9, 0x1600
	v_pk_mul_f32 v[104:105], v[108:109], v[104:105]
	v_pk_mul_f32 v[106:107], v[110:111], v[106:107]
	v_pk_mul_f32 v[96:97], v[100:101], v[96:97]
	v_or_b32_e32 v150, 16, v138
	v_pk_mul_f32 v[98:99], v[102:103], v[98:99]
	v_pk_mul_f32 v[88:89], v[92:93], v[88:89]
	v_pk_mul_f32 v[90:91], v[94:95], v[90:91]
	v_pk_mul_f32 v[80:81], v[84:85], v[80:81]
	v_or_b32_e32 v148, 32, v138
	v_pk_mul_f32 v[82:83], v[86:87], v[82:83]
	v_pk_mul_f32 v[72:73], v[76:77], v[72:73]
	v_pk_mul_f32 v[74:75], v[78:79], v[74:75]
	v_pk_mul_f32 v[64:65], v[68:69], v[64:65]
	v_or_b32_e32 v139, 48, v138
	v_pk_mul_f32 v[66:67], v[70:71], v[66:67]
	v_pk_mul_f32 v[56:57], v[60:61], v[56:57]
	v_pk_mul_f32 v[58:59], v[62:63], v[58:59]
	v_pk_mul_f32 v[48:49], v[52:53], v[48:49]
	v_pk_mul_f32 v[50:51], v[54:55], v[50:51]
	v_pk_mul_f32 v[40:41], v[44:45], v[40:41]
	v_pk_mul_f32 v[42:43], v[46:47], v[42:43]
	v_pk_mul_f32 v[32:33], v[36:37], v[32:33]
	v_pk_mul_f32 v[34:35], v[38:39], v[34:35]
	v_pk_mul_f32 v[24:25], v[28:29], v[24:25]
	v_pk_mul_f32 v[26:27], v[30:31], v[26:27]
	v_pk_mul_f32 v[16:17], v[20:21], v[16:17]
	v_pk_mul_f32 v[18:19], v[22:23], v[18:19]
	v_pk_mul_f32 v[8:9], v[12:13], v[8:9]
	v_pk_mul_f32 v[10:11], v[14:15], v[10:11]
	v_pk_mul_f32 v[0:1], v[4:5], v[0:1]
	v_pk_mul_f32 v[2:3], v[6:7], v[2:3]
	s_mov_b32 s16, s8
	s_mov_b64 s[18:19], s[14:15]
	s_mov_b64 s[20:21], s[12:13]
	v_fmamk_f32 v144, v231, 0x3a800000, v194
	v_cmp_gt_f32_e32 vcc, s2, v144
	v_mul_f32_e32 v152, 0x4b800000, v144
	s_nop 0
	v_cndmask_b32_e32 v144, v144, v152, vcc
	v_rsq_f32_e32 v144, v144
	s_nop 0
	v_mul_f32_e32 v152, 0x45800000, v144
	v_cndmask_b32_e32 v144, v144, v152, vcc
	v_mul_f32_e32 v152, 0xbfb8aa3b, v144
	v_pk_mul_f32 v[156:157], v[124:125], v[152:153] op_sel_hi:[1,0]
	v_pk_mul_f32 v[154:155], v[126:127], v[152:153] op_sel_hi:[1,0]
	v_exp_f32_e32 v153, v156
	v_mul_f32_e32 v144, v144, v144
	v_add_f32_e32 v153, 1.0, v153
	v_rcp_f32_e32 v156, v153
	v_exp_f32_e32 v153, v157
	s_nop 0
	v_add_f32_e32 v153, 1.0, v153
	v_rcp_f32_e32 v157, v153
	v_exp_f32_e32 v153, v154
	v_pk_mul_f32 v[124:125], v[144:145], v[156:157] op_sel_hi:[0,1]
	v_add_f32_e32 v153, 1.0, v153
	v_rcp_f32_e32 v154, v153
	v_exp_f32_e32 v153, v155
	v_pk_mul_f32 v[120:121], v[120:121], v[124:125]
	v_add_f32_e32 v153, 1.0, v153
	v_rcp_f32_e32 v155, v153
	v_cvt_pk_bf16_f32 v124, v121, s0
	v_cvt_pk_bf16_f32 v120, v120, s0
	v_readlane_b32 s0, v254, 29
	v_pk_mul_f32 v[126:127], v[144:145], v[154:155] op_sel_hi:[0,1]
	v_pk_mul_f32 v[122:123], v[122:123], v[126:127]
	v_readlane_b32 s1, v254, 30
	v_cvt_pk_bf16_f32 v121, v122, v123
	v_lshlrev_b32_e32 v122, 16, v124
	v_pk_mul_f32 v[124:125], v[116:117], v[152:153] op_sel_hi:[1,0]
	v_or_b32_sdwa v120, v122, v120 dst_sel:DWORD dst_unused:UNUSED_PAD src0_sel:DWORD src1_sel:WORD_0
	v_pk_mul_f32 v[122:123], v[118:119], v[152:153] op_sel_hi:[1,0]
	v_exp_f32_e32 v124, v124
	v_exp_f32_e32 v125, v125
	v_exp_f32_e32 v122, v122
	v_exp_f32_e32 v123, v123
	v_add_f32_e32 v124, 1.0, v124
	v_add_f32_e32 v125, 1.0, v125
	v_rcp_f32_e32 v124, v124
	v_rcp_f32_e32 v125, v125
	v_add_f32_e32 v122, 1.0, v122
	v_add_f32_e32 v123, 1.0, v123
	v_rcp_f32_e32 v122, v122
	v_rcp_f32_e32 v123, v123
	v_pk_mul_f32 v[116:117], v[144:145], v[124:125] op_sel_hi:[0,1]
	v_pk_mul_f32 v[112:113], v[112:113], v[116:117]
	v_pk_mul_f32 v[118:119], v[144:145], v[122:123] op_sel_hi:[0,1]
	v_pk_mul_f32 v[114:115], v[114:115], v[118:119]
	v_cvt_pk_bf16_f32 v122, v112, v113
	v_mov_b64_e32 v[112:113], s[0:1]
	v_cvt_pk_bf16_f32 v123, v114, v115
	v_mad_i64_i32 v[116:117], s[0:1], v138, s9, v[112:113]
	v_lshlrev_b64 v[114:115], 1, v[142:143]
	v_lshl_add_u64 v[116:117], v[116:117], 0, v[114:115]
	global_store_dwordx4 v[116:117], v[120:123], off
	v_fmamk_f32 v116, v232, 0x3a800000, v194
	v_cmp_gt_f32_e32 vcc, s2, v116
	v_mul_f32_e32 v117, 0x4b800000, v116
	s_nop 0
	v_cndmask_b32_e32 v116, v116, v117, vcc
	v_rsq_f32_e32 v116, v116
	s_nop 0
	v_mul_f32_e32 v117, 0x45800000, v116
	v_cndmask_b32_e32 v116, v116, v117, vcc
	v_mul_f32_e32 v118, 0xbfb8aa3b, v116
	v_pk_mul_f32 v[120:121], v[108:109], v[118:119] op_sel_hi:[1,0]
	v_pk_mul_f32 v[122:123], v[110:111], v[118:119] op_sel_hi:[1,0]
	v_exp_f32_e32 v117, v120
	v_mul_f32_e32 v116, v116, v116
	v_add_f32_e32 v117, 1.0, v117
	v_rcp_f32_e32 v120, v117
	v_exp_f32_e32 v117, v121
	s_nop 0
	v_add_f32_e32 v117, 1.0, v117
	v_rcp_f32_e32 v121, v117
	v_exp_f32_e32 v117, v122
	s_nop 0
	v_add_f32_e32 v117, 1.0, v117
	v_rcp_f32_e32 v122, v117
	v_exp_f32_e32 v117, v123
	s_nop 0
	v_add_f32_e32 v117, 1.0, v117
	v_rcp_f32_e32 v123, v117
	v_pk_mul_f32 v[108:109], v[116:117], v[120:121] op_sel_hi:[0,1]
	v_pk_mul_f32 v[104:105], v[104:105], v[108:109]
	v_pk_mul_f32 v[110:111], v[116:117], v[122:123] op_sel_hi:[0,1]
	v_pk_mul_f32 v[106:107], v[106:107], v[110:111]
	v_cvt_pk_bf16_f32 v108, v105, s0
	v_cvt_pk_bf16_f32 v104, v104, s0
	v_cvt_pk_bf16_f32 v105, v106, v107
	v_lshlrev_b32_e32 v106, 16, v108
	v_pk_mul_f32 v[108:109], v[100:101], v[118:119] op_sel_hi:[1,0]
	v_or_b32_sdwa v104, v106, v104 dst_sel:DWORD dst_unused:UNUSED_PAD src0_sel:DWORD src1_sel:WORD_0
	v_pk_mul_f32 v[106:107], v[102:103], v[118:119] op_sel_hi:[1,0]
	v_exp_f32_e32 v108, v108
	v_exp_f32_e32 v109, v109
	v_exp_f32_e32 v106, v106
	v_exp_f32_e32 v107, v107
	v_add_f32_e32 v108, 1.0, v108
	v_add_f32_e32 v109, 1.0, v109
	v_rcp_f32_e32 v108, v108
	v_rcp_f32_e32 v109, v109
	v_add_f32_e32 v106, 1.0, v106
	v_add_f32_e32 v107, 1.0, v107
	v_rcp_f32_e32 v106, v106
	v_rcp_f32_e32 v107, v107
	v_pk_mul_f32 v[100:101], v[116:117], v[108:109] op_sel_hi:[0,1]
	v_pk_mul_f32 v[96:97], v[96:97], v[100:101]
	v_pk_mul_f32 v[102:103], v[116:117], v[106:107] op_sel_hi:[0,1]
	v_pk_mul_f32 v[98:99], v[98:99], v[102:103]
	v_cvt_pk_bf16_f32 v106, v96, v97
	v_mad_i64_i32 v[96:97], s[0:1], v150, s9, v[112:113]
	v_cvt_pk_bf16_f32 v107, v98, v99
	v_lshl_add_u64 v[96:97], v[96:97], 0, v[114:115]
	global_store_dwordx4 v[96:97], v[104:107], off
	v_fmamk_f32 v96, v233, 0x3a800000, v194
	v_cmp_gt_f32_e32 vcc, s2, v96
	v_mul_f32_e32 v97, 0x4b800000, v96
	s_nop 0
	v_cndmask_b32_e32 v96, v96, v97, vcc
	v_rsq_f32_e32 v96, v96
	s_nop 0
	v_mul_f32_e32 v97, 0x45800000, v96
	v_cndmask_b32_e32 v97, v96, v97, vcc
	v_mul_f32_e32 v96, 0xbfb8aa3b, v97
	v_pk_mul_f32 v[102:103], v[92:93], v[96:97] op_sel_hi:[1,0]
	v_mul_f32_e32 v98, v97, v97
	v_pk_mul_f32 v[100:101], v[94:95], v[96:97] op_sel_hi:[1,0]
	v_exp_f32_e32 v97, v102
	s_nop 0
	v_add_f32_e32 v97, 1.0, v97
	v_rcp_f32_e32 v102, v97
	v_exp_f32_e32 v97, v103
	s_nop 0
	v_add_f32_e32 v97, 1.0, v97
	v_rcp_f32_e32 v103, v97
	v_exp_f32_e32 v97, v100
	v_pk_mul_f32 v[92:93], v[98:99], v[102:103] op_sel_hi:[0,1]
	v_add_f32_e32 v97, 1.0, v97
	v_rcp_f32_e32 v100, v97
	v_exp_f32_e32 v97, v101
	v_pk_mul_f32 v[88:89], v[88:89], v[92:93]
	v_add_f32_e32 v97, 1.0, v97
	v_rcp_f32_e32 v101, v97
	v_cvt_pk_bf16_f32 v92, v89, s0
	v_cvt_pk_bf16_f32 v88, v88, s0
	v_pk_mul_f32 v[94:95], v[98:99], v[100:101] op_sel_hi:[0,1]
	v_pk_mul_f32 v[90:91], v[90:91], v[94:95]
	s_nop 0
	v_cvt_pk_bf16_f32 v89, v90, v91
	v_lshlrev_b32_e32 v90, 16, v92
	v_pk_mul_f32 v[92:93], v[84:85], v[96:97] op_sel_hi:[1,0]
	v_or_b32_sdwa v88, v90, v88 dst_sel:DWORD dst_unused:UNUSED_PAD src0_sel:DWORD src1_sel:WORD_0
	v_pk_mul_f32 v[90:91], v[86:87], v[96:97] op_sel_hi:[1,0]
	v_exp_f32_e32 v92, v92
	v_exp_f32_e32 v93, v93
	v_exp_f32_e32 v90, v90
	v_exp_f32_e32 v91, v91
	v_add_f32_e32 v92, 1.0, v92
	v_add_f32_e32 v93, 1.0, v93
	v_rcp_f32_e32 v92, v92
	v_rcp_f32_e32 v93, v93
	v_add_f32_e32 v90, 1.0, v90
	v_add_f32_e32 v91, 1.0, v91
	v_rcp_f32_e32 v90, v90
	v_rcp_f32_e32 v91, v91
	v_pk_mul_f32 v[84:85], v[98:99], v[92:93] op_sel_hi:[0,1]
	v_pk_mul_f32 v[80:81], v[80:81], v[84:85]
	v_pk_mul_f32 v[86:87], v[98:99], v[90:91] op_sel_hi:[0,1]
	v_pk_mul_f32 v[82:83], v[82:83], v[86:87]
	v_cvt_pk_bf16_f32 v90, v80, v81
	v_mad_i64_i32 v[80:81], s[0:1], v148, s9, v[112:113]
	v_cvt_pk_bf16_f32 v91, v82, v83
	v_lshl_add_u64 v[80:81], v[80:81], 0, v[114:115]
	global_store_dwordx4 v[80:81], v[88:91], off
	v_fmamk_f32 v80, v234, 0x3a800000, v194
	v_cmp_gt_f32_e32 vcc, s2, v80
	v_mul_f32_e32 v81, 0x4b800000, v80
	s_nop 0
	v_cndmask_b32_e32 v80, v80, v81, vcc
	v_rsq_f32_e32 v80, v80
	s_nop 0
	v_mul_f32_e32 v81, 0x45800000, v80
	v_cndmask_b32_e32 v81, v80, v81, vcc
	v_mul_f32_e32 v80, 0xbfb8aa3b, v81
	v_pk_mul_f32 v[86:87], v[76:77], v[80:81] op_sel_hi:[1,0]
	v_mul_f32_e32 v82, v81, v81
	v_pk_mul_f32 v[84:85], v[78:79], v[80:81] op_sel_hi:[1,0]
	v_exp_f32_e32 v81, v86
	s_nop 0
	v_add_f32_e32 v81, 1.0, v81
	v_rcp_f32_e32 v86, v81
	v_exp_f32_e32 v81, v87
	s_nop 0
	v_add_f32_e32 v81, 1.0, v81
	v_rcp_f32_e32 v87, v81
	v_exp_f32_e32 v81, v84
	v_pk_mul_f32 v[76:77], v[82:83], v[86:87] op_sel_hi:[0,1]
	v_add_f32_e32 v81, 1.0, v81
	v_rcp_f32_e32 v84, v81
	v_exp_f32_e32 v81, v85
	v_pk_mul_f32 v[72:73], v[72:73], v[76:77]
	v_add_f32_e32 v81, 1.0, v81
	v_rcp_f32_e32 v85, v81
	v_cvt_pk_bf16_f32 v76, v73, s0
	v_cvt_pk_bf16_f32 v72, v72, s0
	v_pk_mul_f32 v[78:79], v[82:83], v[84:85] op_sel_hi:[0,1]
	v_pk_mul_f32 v[74:75], v[74:75], v[78:79]
	s_nop 0
	v_cvt_pk_bf16_f32 v73, v74, v75
	v_lshlrev_b32_e32 v74, 16, v76
	v_pk_mul_f32 v[76:77], v[68:69], v[80:81] op_sel_hi:[1,0]
	v_or_b32_sdwa v72, v74, v72 dst_sel:DWORD dst_unused:UNUSED_PAD src0_sel:DWORD src1_sel:WORD_0
	v_pk_mul_f32 v[74:75], v[70:71], v[80:81] op_sel_hi:[1,0]
	v_exp_f32_e32 v76, v76
	v_exp_f32_e32 v77, v77
	v_exp_f32_e32 v74, v74
	v_exp_f32_e32 v75, v75
	v_add_f32_e32 v76, 1.0, v76
	v_add_f32_e32 v77, 1.0, v77
	v_rcp_f32_e32 v76, v76
	v_rcp_f32_e32 v77, v77
	v_add_f32_e32 v74, 1.0, v74
	v_add_f32_e32 v75, 1.0, v75
	v_rcp_f32_e32 v74, v74
	v_rcp_f32_e32 v75, v75
	v_pk_mul_f32 v[68:69], v[82:83], v[76:77] op_sel_hi:[0,1]
	v_pk_mul_f32 v[64:65], v[64:65], v[68:69]
	v_add_u32_e32 v69, 0x90, v138
	v_pk_mul_f32 v[70:71], v[82:83], v[74:75] op_sel_hi:[0,1]
	v_pk_mul_f32 v[66:67], v[66:67], v[70:71]
	v_cvt_pk_bf16_f32 v74, v64, v65
	v_mad_i64_i32 v[64:65], s[0:1], v139, s9, v[112:113]
	v_cvt_pk_bf16_f32 v75, v66, v67
	v_lshl_add_u64 v[64:65], v[64:65], 0, v[114:115]
	global_store_dwordx4 v[64:65], v[72:75], off
	v_add_u32_e32 v67, 0x80, v138
	v_add_u32_e32 v66, 0xa0, v138
	v_add_u32_e32 v64, 0xb0, v138
	v_fmamk_f32 v68, v235, 0x3a800000, v194
	v_cmp_gt_f32_e32 vcc, s2, v68
	v_mul_f32_e32 v70, 0x4b800000, v68
	s_nop 0
	v_cndmask_b32_e32 v68, v68, v70, vcc
	v_rsq_f32_e32 v68, v68
	s_nop 0
	v_mul_f32_e32 v70, 0x45800000, v68
	v_cndmask_b32_e32 v70, v68, v70, vcc
	v_mul_f32_e32 v68, 0xbfb8aa3b, v70
	v_pk_mul_f32 v[74:75], v[60:61], v[68:69] op_sel_hi:[1,0]
	v_pk_mul_f32 v[72:73], v[62:63], v[68:69] op_sel_hi:[1,0]
	v_exp_f32_e32 v74, v74
	v_exp_f32_e32 v75, v75
	v_exp_f32_e32 v72, v72
	v_exp_f32_e32 v73, v73
	v_add_f32_e32 v74, 1.0, v74
	v_add_f32_e32 v75, 1.0, v75
	v_rcp_f32_e32 v74, v74
	v_rcp_f32_e32 v75, v75
	v_add_f32_e32 v72, 1.0, v72
	v_add_f32_e32 v73, 1.0, v73
	v_rcp_f32_e32 v72, v72
	v_rcp_f32_e32 v73, v73
	v_mul_f32_e32 v70, v70, v70
	v_pk_mul_f32 v[60:61], v[70:71], v[74:75] op_sel_hi:[0,1]
	v_pk_mul_f32 v[56:57], v[56:57], v[60:61]
	v_pk_mul_f32 v[62:63], v[70:71], v[72:73] op_sel_hi:[0,1]
	v_pk_mul_f32 v[58:59], v[58:59], v[62:63]
	v_cvt_pk_bf16_f32 v60, v57, s0
	v_cvt_pk_bf16_f32 v56, v56, s0
	v_cvt_pk_bf16_f32 v57, v58, v59
	v_lshlrev_b32_e32 v58, 16, v60
	v_pk_mul_f32 v[60:61], v[52:53], v[68:69] op_sel_hi:[1,0]
	v_or_b32_sdwa v56, v58, v56 dst_sel:DWORD dst_unused:UNUSED_PAD src0_sel:DWORD src1_sel:WORD_0
	v_pk_mul_f32 v[58:59], v[54:55], v[68:69] op_sel_hi:[1,0]
	v_exp_f32_e32 v60, v60
	v_exp_f32_e32 v61, v61
	v_exp_f32_e32 v58, v58
	v_exp_f32_e32 v59, v59
	v_add_f32_e32 v60, 1.0, v60
	v_add_f32_e32 v61, 1.0, v61
	v_rcp_f32_e32 v60, v60
	v_rcp_f32_e32 v61, v61
	v_add_f32_e32 v58, 1.0, v58
	v_add_f32_e32 v59, 1.0, v59
	v_rcp_f32_e32 v58, v58
	v_rcp_f32_e32 v59, v59
	v_pk_mul_f32 v[52:53], v[70:71], v[60:61] op_sel_hi:[0,1]
	v_pk_mul_f32 v[48:49], v[48:49], v[52:53]
	v_pk_mul_f32 v[54:55], v[70:71], v[58:59] op_sel_hi:[0,1]
	v_pk_mul_f32 v[50:51], v[50:51], v[54:55]
	v_cvt_pk_bf16_f32 v58, v48, v49
	v_mad_i64_i32 v[48:49], s[0:1], v67, s9, v[112:113]
	v_cvt_pk_bf16_f32 v59, v50, v51
	v_lshl_add_u64 v[48:49], v[48:49], 0, v[114:115]
	global_store_dwordx4 v[48:49], v[56:59], off
	v_fmamk_f32 v48, v236, 0x3a800000, v194
	v_cmp_gt_f32_e32 vcc, s2, v48
	v_mul_f32_e32 v49, 0x4b800000, v48
	s_nop 0
	v_cndmask_b32_e32 v48, v48, v49, vcc
	v_rsq_f32_e32 v48, v48
	s_nop 0
	v_mul_f32_e32 v49, 0x45800000, v48
	v_cndmask_b32_e32 v49, v48, v49, vcc
	v_mul_f32_e32 v48, 0xbfb8aa3b, v49
	v_pk_mul_f32 v[54:55], v[44:45], v[48:49] op_sel_hi:[1,0]
	v_mul_f32_e32 v50, v49, v49
	v_pk_mul_f32 v[52:53], v[46:47], v[48:49] op_sel_hi:[1,0]
	v_exp_f32_e32 v49, v54
	s_nop 0
	v_add_f32_e32 v49, 1.0, v49
	v_rcp_f32_e32 v54, v49
	v_exp_f32_e32 v49, v55
	s_nop 0
	v_add_f32_e32 v49, 1.0, v49
	v_rcp_f32_e32 v55, v49
	v_exp_f32_e32 v49, v52
	v_pk_mul_f32 v[44:45], v[50:51], v[54:55] op_sel_hi:[0,1]
	v_add_f32_e32 v49, 1.0, v49
	v_rcp_f32_e32 v52, v49
	v_exp_f32_e32 v49, v53
	v_pk_mul_f32 v[40:41], v[40:41], v[44:45]
	v_add_f32_e32 v49, 1.0, v49
	v_rcp_f32_e32 v53, v49
	v_cvt_pk_bf16_f32 v44, v41, s0
	v_cvt_pk_bf16_f32 v40, v40, s0
	v_pk_mul_f32 v[46:47], v[50:51], v[52:53] op_sel_hi:[0,1]
	v_pk_mul_f32 v[42:43], v[42:43], v[46:47]
	s_nop 0
	v_cvt_pk_bf16_f32 v41, v42, v43
	v_lshlrev_b32_e32 v42, 16, v44
	v_pk_mul_f32 v[44:45], v[36:37], v[48:49] op_sel_hi:[1,0]
	v_or_b32_sdwa v40, v42, v40 dst_sel:DWORD dst_unused:UNUSED_PAD src0_sel:DWORD src1_sel:WORD_0
	v_pk_mul_f32 v[42:43], v[38:39], v[48:49] op_sel_hi:[1,0]
	v_exp_f32_e32 v44, v44
	v_exp_f32_e32 v45, v45
	v_exp_f32_e32 v42, v42
	v_exp_f32_e32 v43, v43
	v_add_f32_e32 v44, 1.0, v44
	v_add_f32_e32 v45, 1.0, v45
	v_rcp_f32_e32 v44, v44
	v_rcp_f32_e32 v45, v45
	v_add_f32_e32 v42, 1.0, v42
	v_add_f32_e32 v43, 1.0, v43
	v_rcp_f32_e32 v42, v42
	v_rcp_f32_e32 v43, v43
	v_pk_mul_f32 v[36:37], v[50:51], v[44:45] op_sel_hi:[0,1]
	v_pk_mul_f32 v[32:33], v[32:33], v[36:37]
	v_pk_mul_f32 v[38:39], v[50:51], v[42:43] op_sel_hi:[0,1]
	v_pk_mul_f32 v[34:35], v[34:35], v[38:39]
	v_cvt_pk_bf16_f32 v42, v32, v33
	v_mad_i64_i32 v[32:33], s[0:1], v69, s9, v[112:113]
	v_cvt_pk_bf16_f32 v43, v34, v35
	v_lshl_add_u64 v[32:33], v[32:33], 0, v[114:115]
	global_store_dwordx4 v[32:33], v[40:43], off
	v_fmamk_f32 v32, v237, 0x3a800000, v194
	v_cmp_gt_f32_e32 vcc, s2, v32
	v_mul_f32_e32 v33, 0x4b800000, v32
	s_nop 0
	v_cndmask_b32_e32 v32, v32, v33, vcc
	v_rsq_f32_e32 v32, v32
	s_nop 0
	v_mul_f32_e32 v33, 0x45800000, v32
	v_cndmask_b32_e32 v33, v32, v33, vcc
	v_mul_f32_e32 v32, 0xbfb8aa3b, v33
	v_pk_mul_f32 v[38:39], v[28:29], v[32:33] op_sel_hi:[1,0]
	v_mul_f32_e32 v34, v33, v33
	v_pk_mul_f32 v[36:37], v[30:31], v[32:33] op_sel_hi:[1,0]
	v_exp_f32_e32 v33, v38
	s_nop 0
	v_add_f32_e32 v33, 1.0, v33
	v_rcp_f32_e32 v38, v33
	v_exp_f32_e32 v33, v39
	s_nop 0
	v_add_f32_e32 v33, 1.0, v33
	v_rcp_f32_e32 v39, v33
	v_exp_f32_e32 v33, v36
	v_pk_mul_f32 v[28:29], v[34:35], v[38:39] op_sel_hi:[0,1]
	v_add_f32_e32 v33, 1.0, v33
	v_rcp_f32_e32 v36, v33
	v_exp_f32_e32 v33, v37
	v_pk_mul_f32 v[24:25], v[24:25], v[28:29]
	v_add_f32_e32 v33, 1.0, v33
	v_rcp_f32_e32 v37, v33
	v_cvt_pk_bf16_f32 v28, v25, s0
	v_cvt_pk_bf16_f32 v24, v24, s0
	v_pk_mul_f32 v[30:31], v[34:35], v[36:37] op_sel_hi:[0,1]
	v_pk_mul_f32 v[26:27], v[26:27], v[30:31]
	s_nop 0
	v_cvt_pk_bf16_f32 v25, v26, v27
	v_lshlrev_b32_e32 v26, 16, v28
	v_pk_mul_f32 v[28:29], v[20:21], v[32:33] op_sel_hi:[1,0]
	v_or_b32_sdwa v24, v26, v24 dst_sel:DWORD dst_unused:UNUSED_PAD src0_sel:DWORD src1_sel:WORD_0
	v_pk_mul_f32 v[26:27], v[22:23], v[32:33] op_sel_hi:[1,0]
	v_exp_f32_e32 v28, v28
	v_exp_f32_e32 v29, v29
	v_exp_f32_e32 v26, v26
	v_exp_f32_e32 v27, v27
	v_add_f32_e32 v28, 1.0, v28
	v_add_f32_e32 v29, 1.0, v29
	v_rcp_f32_e32 v28, v28
	v_rcp_f32_e32 v29, v29
	v_add_f32_e32 v26, 1.0, v26
	v_add_f32_e32 v27, 1.0, v27
	v_rcp_f32_e32 v26, v26
	v_rcp_f32_e32 v27, v27
	v_pk_mul_f32 v[20:21], v[34:35], v[28:29] op_sel_hi:[0,1]
	v_pk_mul_f32 v[16:17], v[16:17], v[20:21]
	v_pk_mul_f32 v[22:23], v[34:35], v[26:27] op_sel_hi:[0,1]
	v_pk_mul_f32 v[18:19], v[18:19], v[22:23]
	v_cvt_pk_bf16_f32 v26, v16, v17
	v_mad_i64_i32 v[16:17], s[0:1], v66, s9, v[112:113]
	v_cvt_pk_bf16_f32 v27, v18, v19
	v_lshl_add_u64 v[16:17], v[16:17], 0, v[114:115]
	global_store_dwordx4 v[16:17], v[24:27], off
	v_fmamk_f32 v16, v238, 0x3a800000, v194
	v_cmp_gt_f32_e32 vcc, s2, v16
	v_mul_f32_e32 v17, 0x4b800000, v16
	s_nop 0
	v_cndmask_b32_e32 v16, v16, v17, vcc
	v_rsq_f32_e32 v16, v16
	s_nop 0
	v_mul_f32_e32 v17, 0x45800000, v16
	v_cndmask_b32_e32 v17, v16, v17, vcc
	v_mul_f32_e32 v16, 0xbfb8aa3b, v17
	v_pk_mul_f32 v[22:23], v[12:13], v[16:17] op_sel_hi:[1,0]
	v_mul_f32_e32 v18, v17, v17
	v_pk_mul_f32 v[20:21], v[14:15], v[16:17] op_sel_hi:[1,0]
	v_exp_f32_e32 v17, v22
	s_and_b64 vcc, exec, s[4:5]
	v_add_f32_e32 v17, 1.0, v17
	v_rcp_f32_e32 v22, v17
	v_exp_f32_e32 v17, v23
	s_nop 0
	v_add_f32_e32 v17, 1.0, v17
	v_rcp_f32_e32 v23, v17
	v_exp_f32_e32 v17, v20
	v_pk_mul_f32 v[12:13], v[18:19], v[22:23] op_sel_hi:[0,1]
	v_add_f32_e32 v17, 1.0, v17
	v_rcp_f32_e32 v20, v17
	v_exp_f32_e32 v17, v21
	v_pk_mul_f32 v[8:9], v[8:9], v[12:13]
	v_add_f32_e32 v17, 1.0, v17
	v_rcp_f32_e32 v21, v17
	v_cvt_pk_bf16_f32 v12, v9, s0
	v_cvt_pk_bf16_f32 v8, v8, s0
	v_pk_mul_f32 v[14:15], v[18:19], v[20:21] op_sel_hi:[0,1]
	v_pk_mul_f32 v[10:11], v[10:11], v[14:15]
	s_nop 0
	v_cvt_pk_bf16_f32 v9, v10, v11
	v_lshlrev_b32_e32 v10, 16, v12
	v_pk_mul_f32 v[12:13], v[4:5], v[16:17] op_sel_hi:[1,0]
	v_or_b32_sdwa v8, v10, v8 dst_sel:DWORD dst_unused:UNUSED_PAD src0_sel:DWORD src1_sel:WORD_0
	v_pk_mul_f32 v[10:11], v[6:7], v[16:17] op_sel_hi:[1,0]
	v_exp_f32_e32 v12, v12
	v_exp_f32_e32 v13, v13
	v_exp_f32_e32 v10, v10
	v_exp_f32_e32 v11, v11
	v_add_f32_e32 v12, 1.0, v12
	v_add_f32_e32 v13, 1.0, v13
	v_rcp_f32_e32 v12, v12
	v_rcp_f32_e32 v13, v13
	v_add_f32_e32 v10, 1.0, v10
	v_add_f32_e32 v11, 1.0, v11
	v_rcp_f32_e32 v10, v10
	v_rcp_f32_e32 v11, v11
	v_pk_mul_f32 v[4:5], v[18:19], v[12:13] op_sel_hi:[0,1]
	v_pk_mul_f32 v[0:1], v[0:1], v[4:5]
	v_pk_mul_f32 v[6:7], v[18:19], v[10:11] op_sel_hi:[0,1]
	v_pk_mul_f32 v[2:3], v[2:3], v[6:7]
	v_cvt_pk_bf16_f32 v10, v0, v1
	v_mad_i64_i32 v[0:1], s[0:1], v64, s9, v[112:113]
	v_cvt_pk_bf16_f32 v11, v2, v3
	v_lshl_add_u64 v[0:1], v[0:1], 0, v[114:115]
	s_mov_b32 s0, s10
	global_store_dwordx4 v[0:1], v[8:11], off
	s_cbranch_vccz .LBB0_399
	s_waitcnt vmcnt(0)
	s_cmpk_gt_u32 s25, 0xff
	s_cbranch_scc1 .LBB0_406
	s_barrier

.LBB0_1622:
	s_add_u32 s33, s22, 0x100
	v_mov_b32_e32 v0, 0
	s_addc_u32 s44, s23, 0
	s_mov_b32 s45, -2
	v_mov_b32_e32 v1, v0
	v_mov_b32_e32 v2, v0
	v_mov_b32_e32 v3, v0
	v_mov_b32_e32 v4, v0
	v_mov_b32_e32 v5, v0
	v_mov_b32_e32 v6, v0
	v_mov_b32_e32 v7, v0
	v_mov_b32_e32 v16, v0
	v_mov_b32_e32 v17, v0
	v_mov_b32_e32 v18, v0
	v_mov_b32_e32 v19, v0
	v_mov_b32_e32 v20, v0
	v_mov_b32_e32 v21, v0
	v_mov_b32_e32 v22, v0
	v_mov_b32_e32 v23, v0
	v_mov_b32_e32 v32, v0
	v_mov_b32_e32 v33, v0
	v_mov_b32_e32 v34, v0
	v_mov_b32_e32 v35, v0
	v_mov_b32_e32 v36, v0
	v_mov_b32_e32 v37, v0
	v_mov_b32_e32 v38, v0
	v_mov_b32_e32 v39, v0
	v_mov_b32_e32 v48, v0
	v_mov_b32_e32 v49, v0
	v_mov_b32_e32 v50, v0
	v_mov_b32_e32 v51, v0
	v_mov_b32_e32 v52, v0
	v_mov_b32_e32 v53, v0
	v_mov_b32_e32 v54, v0
	v_mov_b32_e32 v55, v0
	v_mov_b32_e32 v8, v0
	v_mov_b32_e32 v9, v0
	v_mov_b32_e32 v10, v0
	v_mov_b32_e32 v11, v0
	v_mov_b32_e32 v12, v0
	v_mov_b32_e32 v13, v0
	v_mov_b32_e32 v14, v0
	v_mov_b32_e32 v15, v0
	v_mov_b32_e32 v24, v0
	v_mov_b32_e32 v25, v0
	v_mov_b32_e32 v26, v0
	v_mov_b32_e32 v27, v0
	v_mov_b32_e32 v28, v0
	v_mov_b32_e32 v29, v0
	v_mov_b32_e32 v30, v0
	v_mov_b32_e32 v31, v0
	v_mov_b32_e32 v40, v0
	v_mov_b32_e32 v41, v0
	v_mov_b32_e32 v42, v0
	v_mov_b32_e32 v43, v0
	v_mov_b32_e32 v44, v0
	v_mov_b32_e32 v45, v0
	v_mov_b32_e32 v46, v0
	v_mov_b32_e32 v47, v0
	v_mov_b32_e32 v56, v0
	v_mov_b32_e32 v57, v0
	v_mov_b32_e32 v58, v0
	v_mov_b32_e32 v59, v0
	v_mov_b32_e32 v60, v0
	v_mov_b32_e32 v61, v0
	v_mov_b32_e32 v62, v0
	v_mov_b32_e32 v63, v0
	s_waitcnt vmcnt(0)
	v_mov_b32_e32 v64, v0
	v_mov_b32_e32 v65, v0
	v_mov_b32_e32 v66, v0
	v_mov_b32_e32 v67, v0
	v_mov_b32_e32 v68, v0
	v_mov_b32_e32 v69, v0
	v_mov_b32_e32 v70, v0
	v_mov_b32_e32 v71, v0
	v_mov_b32_e32 v80, v0
	v_mov_b32_e32 v81, v0
	v_mov_b32_e32 v82, v0
	v_mov_b32_e32 v83, v0
	v_mov_b32_e32 v84, v0
	v_mov_b32_e32 v85, v0
	v_mov_b32_e32 v86, v0
	v_mov_b32_e32 v87, v0
	v_mov_b32_e32 v96, v0
	v_mov_b32_e32 v97, v0
	v_mov_b32_e32 v98, v0
	v_mov_b32_e32 v99, v0
	v_mov_b32_e32 v100, v0
	v_mov_b32_e32 v101, v0
	v_mov_b32_e32 v102, v0
	v_mov_b32_e32 v103, v0
	v_mov_b32_e32 v112, v0
	v_mov_b32_e32 v113, v0
	v_mov_b32_e32 v114, v0
	v_mov_b32_e32 v115, v0
	v_mov_b32_e32 v116, v0
	v_mov_b32_e32 v117, v0
	v_mov_b32_e32 v118, v0
	v_mov_b32_e32 v119, v0
	v_mov_b32_e32 v72, v0
	v_mov_b32_e32 v73, v0
	v_mov_b32_e32 v74, v0
	v_mov_b32_e32 v75, v0
	v_mov_b32_e32 v76, v0
	v_mov_b32_e32 v77, v0
	v_mov_b32_e32 v78, v0
	v_mov_b32_e32 v79, v0
	v_mov_b32_e32 v88, v0
	v_mov_b32_e32 v89, v0
	v_mov_b32_e32 v90, v0
	v_mov_b32_e32 v91, v0
	v_mov_b32_e32 v92, v0
	v_mov_b32_e32 v93, v0
	v_mov_b32_e32 v94, v0
	v_mov_b32_e32 v95, v0
	v_mov_b32_e32 v104, v0
	v_mov_b32_e32 v105, v0
	v_mov_b32_e32 v106, v0
	v_mov_b32_e32 v107, v0
	v_mov_b32_e32 v108, v0
	v_mov_b32_e32 v109, v0
	v_mov_b32_e32 v110, v0
	v_mov_b32_e32 v111, v0
	v_mov_b32_e32 v120, v0
	v_mov_b32_e32 v121, v0
	v_mov_b32_e32 v122, v0
	v_mov_b32_e32 v123, v0
	v_mov_b32_e32 v124, v0
	v_mov_b32_e32 v125, v0
	v_mov_b32_e32 v126, v0
	v_mov_b32_e32 v127, v0
	v_add_u32_e32 v216, 0x10000, v196
	v_add_u32_e32 v217, 0x14000, v196
	v_add_u32_e32 v218, 0x18000, v196
	v_add_u32_e32 v219, 0x1c000, v196
.LBB0_1623:
	s_add_u32 s22, s20, 0x100
	s_addc_u32 s23, s21, 0
	s_add_i32 s46, 0, 0x10000
	ds_read_b128 v[128:131], v216
	ds_read_b128 v[132:135], v216 offset:1024
	ds_read_b128 v[136:139], v216 offset:2048
	ds_read_b128 v[140:143], v216 offset:3072
	s_cmp_eq_u32 s45, 40
	s_cselect_b32 s27, s7, s23
	s_cselect_b32 s26, s6, s22
	s_cselect_b32 s25, s9, s44
	s_cselect_b32 s24, s8, s33
	s_add_i32 m0, s34, 0xc000
	ds_read_b128 v[144:147], v198
	ds_read_b128 v[148:151], v198 offset:1024
	ds_read_b128 v[152:155], v198 offset:2048
	ds_read_b128 v[156:159], v198 offset:3072
	ds_read_b128 v[160:163], v198 offset:4096
	ds_read_b128 v[164:167], v198 offset:5120
	ds_read_b128 v[168:171], v198 offset:6144
	ds_read_b128 v[172:175], v198 offset:7168
	global_load_lds_dwordx4 v214, s[20:21]
	s_add_i32 m0, s34, 0xe000
	s_nop 0
	global_load_lds_dwordx4 v212, s[20:21]
	s_waitcnt lgkmcnt(8)
	s_barrier
	s_waitcnt lgkmcnt(0)
	s_setprio 1
	s_waitcnt lgkmcnt(0)
	v_mfma_f32_16x16x32_bf16 v[124:127], v[128:131], v[144:147], v[124:127]
	v_mfma_f32_16x16x32_bf16 v[120:123], v[136:139], v[144:147], v[120:123]
	v_mfma_f32_16x16x32_bf16 v[108:111], v[128:131], v[152:155], v[108:111]
	v_mfma_f32_16x16x32_bf16 v[104:107], v[136:139], v[152:155], v[104:107]
	v_mfma_f32_16x16x32_bf16 v[92:95], v[128:131], v[160:163], v[92:95]
	v_mfma_f32_16x16x32_bf16 v[88:91], v[136:139], v[160:163], v[88:91]
	v_mfma_f32_16x16x32_bf16 v[76:79], v[128:131], v[168:171], v[76:79]
	v_mfma_f32_16x16x32_bf16 v[72:75], v[136:139], v[168:171], v[72:75]
	v_mfma_f32_16x16x32_bf16 v[124:127], v[132:135], v[148:151], v[124:127]
	v_mfma_f32_16x16x32_bf16 v[120:123], v[140:143], v[148:151], v[120:123]
	v_mfma_f32_16x16x32_bf16 v[108:111], v[132:135], v[156:159], v[108:111]
	v_mfma_f32_16x16x32_bf16 v[104:107], v[140:143], v[156:159], v[104:107]
	v_mfma_f32_16x16x32_bf16 v[92:95], v[132:135], v[164:167], v[92:95]
	v_mfma_f32_16x16x32_bf16 v[88:91], v[140:143], v[164:167], v[88:91]
	v_mfma_f32_16x16x32_bf16 v[76:79], v[132:135], v[172:175], v[76:79]
	v_mfma_f32_16x16x32_bf16 v[72:75], v[140:143], v[172:175], v[72:75]
	s_setprio 0
	s_barrier
	s_add_i32 s47, 0, 0x14000
	s_add_i32 s20, s46, s31
	s_mov_b32 m0, s20
	ds_read_b128 v[176:179], v217
	ds_read_b128 v[180:183], v217 offset:1024
	ds_read_b128 v[184:187], v217 offset:2048
	ds_read_b128 v[188:191], v217 offset:3072
	global_load_lds_dwordx4 v192, s[24:25]
	s_add_i32 m0, s20, 0x2000
	s_nop 0
	global_load_lds_dwordx4 v210, s[24:25]
	s_barrier
	s_waitcnt lgkmcnt(0)
	s_setprio 1
	s_waitcnt lgkmcnt(0)
	v_mfma_f32_16x16x32_bf16 v[116:119], v[176:179], v[144:147], v[116:119]
	v_mfma_f32_16x16x32_bf16 v[112:115], v[184:187], v[144:147], v[112:115]
	v_mfma_f32_16x16x32_bf16 v[100:103], v[176:179], v[152:155], v[100:103]
	v_mfma_f32_16x16x32_bf16 v[96:99], v[184:187], v[152:155], v[96:99]
	v_mfma_f32_16x16x32_bf16 v[84:87], v[176:179], v[160:163], v[84:87]
	v_mfma_f32_16x16x32_bf16 v[80:83], v[184:187], v[160:163], v[80:83]
	v_mfma_f32_16x16x32_bf16 v[68:71], v[176:179], v[168:171], v[68:71]
	v_mfma_f32_16x16x32_bf16 v[64:67], v[184:187], v[168:171], v[64:67]
	v_mfma_f32_16x16x32_bf16 v[116:119], v[180:183], v[148:151], v[116:119]
	v_mfma_f32_16x16x32_bf16 v[112:115], v[188:191], v[148:151], v[112:115]
	v_mfma_f32_16x16x32_bf16 v[100:103], v[180:183], v[156:159], v[100:103]
	v_mfma_f32_16x16x32_bf16 v[96:99], v[188:191], v[156:159], v[96:99]
	v_mfma_f32_16x16x32_bf16 v[84:87], v[180:183], v[164:167], v[84:87]
	v_mfma_f32_16x16x32_bf16 v[80:83], v[188:191], v[164:167], v[80:83]
	v_mfma_f32_16x16x32_bf16 v[68:71], v[180:183], v[172:175], v[68:71]
	v_mfma_f32_16x16x32_bf16 v[64:67], v[188:191], v[172:175], v[64:67]
	s_setprio 0
	s_mov_b32 m0, s34
	s_add_u32 vcc_lo, s26, 0x80
	s_addc_u32 vcc_hi, s27, 0
	s_barrier
	ds_read_b128 v[144:147], v198 offset:16384
	ds_read_b128 v[148:151], v198 offset:17408
	ds_read_b128 v[152:155], v198 offset:18432
	ds_read_b128 v[156:159], v198 offset:19456
	ds_read_b128 v[160:163], v198 offset:20480
	ds_read_b128 v[164:167], v198 offset:21504
	ds_read_b128 v[168:171], v198 offset:22528
	ds_read_b128 v[172:175], v198 offset:23552
	global_load_lds_dwordx4 v206, s[26:27]
	s_mov_b32 m0, s35
	s_nop 0
	global_load_lds_dwordx4 v208, s[26:27]
	s_barrier
	s_waitcnt lgkmcnt(0)
	s_setprio 1
	s_waitcnt lgkmcnt(0)
	v_mfma_f32_16x16x32_bf16 v[60:63], v[128:131], v[144:147], v[60:63]
	v_mfma_f32_16x16x32_bf16 v[56:59], v[136:139], v[144:147], v[56:59]
	v_mfma_f32_16x16x32_bf16 v[44:47], v[128:131], v[152:155], v[44:47]
	v_mfma_f32_16x16x32_bf16 v[40:43], v[136:139], v[152:155], v[40:43]
	v_mfma_f32_16x16x32_bf16 v[28:31], v[128:131], v[160:163], v[28:31]
	v_mfma_f32_16x16x32_bf16 v[24:27], v[136:139], v[160:163], v[24:27]
	v_mfma_f32_16x16x32_bf16 v[12:15], v[128:131], v[168:171], v[12:15]
	v_mfma_f32_16x16x32_bf16 v[8:11], v[136:139], v[168:171], v[8:11]
	v_mfma_f32_16x16x32_bf16 v[60:63], v[132:135], v[148:151], v[60:63]
	v_mfma_f32_16x16x32_bf16 v[56:59], v[140:143], v[148:151], v[56:59]
	v_mfma_f32_16x16x32_bf16 v[44:47], v[132:135], v[156:159], v[44:47]
	v_mfma_f32_16x16x32_bf16 v[40:43], v[140:143], v[156:159], v[40:43]
	v_mfma_f32_16x16x32_bf16 v[28:31], v[132:135], v[164:167], v[28:31]
	v_mfma_f32_16x16x32_bf16 v[24:27], v[140:143], v[164:167], v[24:27]
	v_mfma_f32_16x16x32_bf16 v[12:15], v[132:135], v[172:175], v[12:15]
	v_mfma_f32_16x16x32_bf16 v[8:11], v[140:143], v[172:175], v[8:11]
	s_setprio 0
	s_barrier
	s_add_u32 s20, s24, 0xb0000
	s_addc_u32 s21, s25, 0
	s_add_i32 s46, s47, s31
	s_mov_b32 m0, s46
	s_nop 0
	global_load_lds_dwordx4 v192, s[20:21]
	s_add_i32 m0, s46, 0x2000
	s_nop 0
	global_load_lds_dwordx4 v210, s[20:21]
	s_waitcnt vmcnt(6)
	s_barrier
	s_setprio 1
	v_mfma_f32_16x16x32_bf16 v[52:55], v[176:179], v[144:147], v[52:55]
	v_mfma_f32_16x16x32_bf16 v[48:51], v[184:187], v[144:147], v[48:51]
	v_mfma_f32_16x16x32_bf16 v[36:39], v[176:179], v[152:155], v[36:39]
	v_mfma_f32_16x16x32_bf16 v[32:35], v[184:187], v[152:155], v[32:35]
	v_mfma_f32_16x16x32_bf16 v[20:23], v[176:179], v[160:163], v[20:23]
	v_mfma_f32_16x16x32_bf16 v[16:19], v[184:187], v[160:163], v[16:19]
	v_mfma_f32_16x16x32_bf16 v[4:7], v[176:179], v[168:171], v[4:7]
	v_mfma_f32_16x16x32_bf16 v[0:3], v[184:187], v[168:171], v[0:3]
	v_mfma_f32_16x16x32_bf16 v[52:55], v[180:183], v[148:151], v[52:55]
	v_mfma_f32_16x16x32_bf16 v[48:51], v[188:191], v[148:151], v[48:51]
	v_mfma_f32_16x16x32_bf16 v[36:39], v[180:183], v[156:159], v[36:39]
	v_mfma_f32_16x16x32_bf16 v[32:35], v[188:191], v[156:159], v[32:35]
	v_mfma_f32_16x16x32_bf16 v[20:23], v[180:183], v[164:167], v[20:23]
	v_mfma_f32_16x16x32_bf16 v[16:19], v[188:191], v[164:167], v[16:19]
	v_mfma_f32_16x16x32_bf16 v[4:7], v[180:183], v[172:175], v[4:7]
	v_mfma_f32_16x16x32_bf16 v[0:3], v[188:191], v[172:175], v[0:3]
	s_setprio 0
	s_add_i32 s46, 0, 0x18000
	s_barrier
	ds_read_b128 v[128:131], v218
	ds_read_b128 v[132:135], v218 offset:1024
	ds_read_b128 v[136:139], v218 offset:2048
	ds_read_b128 v[140:143], v218 offset:3072
	s_add_u32 s20, s26, 0xb0000
	s_addc_u32 s21, s27, 0
	s_mov_b32 m0, s36
	ds_read_b128 v[144:147], v198 offset:32768
	ds_read_b128 v[148:151], v198 offset:33792
	ds_read_b128 v[152:155], v198 offset:34816
	ds_read_b128 v[156:159], v198 offset:35840
	ds_read_b128 v[160:163], v198 offset:36864
	ds_read_b128 v[164:167], v198 offset:37888
	ds_read_b128 v[168:171], v198 offset:38912
	ds_read_b128 v[172:175], v198 offset:39936
	global_load_lds_dwordx4 v206, s[20:21]
	s_mov_b32 m0, s37
	s_nop 0
	global_load_lds_dwordx4 v208, s[20:21]
	s_waitcnt lgkmcnt(8)
	s_barrier
	s_waitcnt lgkmcnt(0)
	s_setprio 1
	s_waitcnt lgkmcnt(0)
	v_mfma_f32_16x16x32_bf16 v[124:127], v[128:131], v[144:147], v[124:127]
	v_mfma_f32_16x16x32_bf16 v[120:123], v[136:139], v[144:147], v[120:123]
	v_mfma_f32_16x16x32_bf16 v[108:111], v[128:131], v[152:155], v[108:111]
	v_mfma_f32_16x16x32_bf16 v[104:107], v[136:139], v[152:155], v[104:107]
	v_mfma_f32_16x16x32_bf16 v[92:95], v[128:131], v[160:163], v[92:95]
	v_mfma_f32_16x16x32_bf16 v[88:91], v[136:139], v[160:163], v[88:91]
	v_mfma_f32_16x16x32_bf16 v[76:79], v[128:131], v[168:171], v[76:79]
	v_mfma_f32_16x16x32_bf16 v[72:75], v[136:139], v[168:171], v[72:75]
	v_mfma_f32_16x16x32_bf16 v[124:127], v[132:135], v[148:151], v[124:127]
	v_mfma_f32_16x16x32_bf16 v[120:123], v[140:143], v[148:151], v[120:123]
	v_mfma_f32_16x16x32_bf16 v[108:111], v[132:135], v[156:159], v[108:111]
	v_mfma_f32_16x16x32_bf16 v[104:107], v[140:143], v[156:159], v[104:107]
	v_mfma_f32_16x16x32_bf16 v[92:95], v[132:135], v[164:167], v[92:95]
	v_mfma_f32_16x16x32_bf16 v[88:91], v[140:143], v[164:167], v[88:91]
	v_mfma_f32_16x16x32_bf16 v[76:79], v[132:135], v[172:175], v[76:79]
	v_mfma_f32_16x16x32_bf16 v[72:75], v[140:143], v[172:175], v[72:75]
	s_setprio 0
	s_barrier
	s_add_i32 s26, 0, 0x1c000
	s_add_i32 s20, s46, s31
	s_add_u32 s100, s24, 0x80
	s_addc_u32 s101, s25, 0
	s_mov_b32 m0, s20
	ds_read_b128 v[176:179], v219
	ds_read_b128 v[180:183], v219 offset:1024
	ds_read_b128 v[184:187], v219 offset:2048
	ds_read_b128 v[188:191], v219 offset:3072
	global_load_lds_dwordx4 v192, s[100:101]
	s_add_i32 m0, s20, 0x2000
	s_nop 0
	global_load_lds_dwordx4 v210, s[100:101]
	s_barrier
	s_waitcnt lgkmcnt(0)
	s_setprio 1
	s_waitcnt lgkmcnt(0)
	v_mfma_f32_16x16x32_bf16 v[116:119], v[176:179], v[144:147], v[116:119]
	v_mfma_f32_16x16x32_bf16 v[112:115], v[184:187], v[144:147], v[112:115]
	v_mfma_f32_16x16x32_bf16 v[100:103], v[176:179], v[152:155], v[100:103]
	v_mfma_f32_16x16x32_bf16 v[96:99], v[184:187], v[152:155], v[96:99]
	v_mfma_f32_16x16x32_bf16 v[84:87], v[176:179], v[160:163], v[84:87]
	v_mfma_f32_16x16x32_bf16 v[80:83], v[184:187], v[160:163], v[80:83]
	v_mfma_f32_16x16x32_bf16 v[68:71], v[176:179], v[168:171], v[68:71]
	v_mfma_f32_16x16x32_bf16 v[64:67], v[184:187], v[168:171], v[64:67]
	v_mfma_f32_16x16x32_bf16 v[116:119], v[180:183], v[148:151], v[116:119]
	v_mfma_f32_16x16x32_bf16 v[112:115], v[188:191], v[148:151], v[112:115]
	v_mfma_f32_16x16x32_bf16 v[100:103], v[180:183], v[156:159], v[100:103]
	v_mfma_f32_16x16x32_bf16 v[96:99], v[188:191], v[156:159], v[96:99]
	v_mfma_f32_16x16x32_bf16 v[84:87], v[180:183], v[164:167], v[84:87]
	v_mfma_f32_16x16x32_bf16 v[80:83], v[188:191], v[164:167], v[80:83]
	v_mfma_f32_16x16x32_bf16 v[68:71], v[180:183], v[172:175], v[68:71]
	v_mfma_f32_16x16x32_bf16 v[64:67], v[188:191], v[172:175], v[64:67]
	s_setprio 0
	s_mov_b32 m0, s38
	s_barrier
	ds_read_b128 v[144:147], v198 offset:49152
	ds_read_b128 v[148:151], v198 offset:50176
	ds_read_b128 v[152:155], v198 offset:51200
	ds_read_b128 v[156:159], v198 offset:52224
	ds_read_b128 v[160:163], v198 offset:53248
	ds_read_b128 v[164:167], v198 offset:54272
	ds_read_b128 v[168:171], v198 offset:55296
	ds_read_b128 v[172:175], v198 offset:56320
	global_load_lds_dwordx4 v206, vcc
	s_mov_b32 m0, s39
	s_nop 0
	global_load_lds_dwordx4 v208, vcc
	s_barrier
	s_waitcnt lgkmcnt(0)
	s_setprio 1
	s_waitcnt lgkmcnt(0)
	v_mfma_f32_16x16x32_bf16 v[60:63], v[128:131], v[144:147], v[60:63]
	v_mfma_f32_16x16x32_bf16 v[56:59], v[136:139], v[144:147], v[56:59]
	v_mfma_f32_16x16x32_bf16 v[44:47], v[128:131], v[152:155], v[44:47]
	v_mfma_f32_16x16x32_bf16 v[40:43], v[136:139], v[152:155], v[40:43]
	v_mfma_f32_16x16x32_bf16 v[28:31], v[128:131], v[160:163], v[28:31]
	v_mfma_f32_16x16x32_bf16 v[24:27], v[136:139], v[160:163], v[24:27]
	v_mfma_f32_16x16x32_bf16 v[12:15], v[128:131], v[168:171], v[12:15]
	v_mfma_f32_16x16x32_bf16 v[8:11], v[136:139], v[168:171], v[8:11]
	v_mfma_f32_16x16x32_bf16 v[60:63], v[132:135], v[148:151], v[60:63]
	v_mfma_f32_16x16x32_bf16 v[56:59], v[140:143], v[148:151], v[56:59]
	v_mfma_f32_16x16x32_bf16 v[44:47], v[132:135], v[156:159], v[44:47]
	v_mfma_f32_16x16x32_bf16 v[40:43], v[140:143], v[156:159], v[40:43]
	v_mfma_f32_16x16x32_bf16 v[28:31], v[132:135], v[164:167], v[28:31]
	v_mfma_f32_16x16x32_bf16 v[24:27], v[140:143], v[164:167], v[24:27]
	v_mfma_f32_16x16x32_bf16 v[12:15], v[132:135], v[172:175], v[12:15]
	v_mfma_f32_16x16x32_bf16 v[8:11], v[140:143], v[172:175], v[8:11]
	s_setprio 0
	s_barrier
	s_add_u32 s20, s24, 0xb0080
	s_addc_u32 s21, s25, 0
	s_add_i32 s24, s26, s31
	s_mov_b32 m0, s24
	s_nop 0
	global_load_lds_dwordx4 v192, s[20:21]
	s_add_i32 m0, s24, 0x2000
	s_nop 0
	global_load_lds_dwordx4 v210, s[20:21]
	s_waitcnt vmcnt(6)
	s_barrier
	s_setprio 1
	v_mfma_f32_16x16x32_bf16 v[52:55], v[176:179], v[144:147], v[52:55]
	v_mfma_f32_16x16x32_bf16 v[48:51], v[184:187], v[144:147], v[48:51]
	v_mfma_f32_16x16x32_bf16 v[36:39], v[176:179], v[152:155], v[36:39]
	v_mfma_f32_16x16x32_bf16 v[32:35], v[184:187], v[152:155], v[32:35]
	v_mfma_f32_16x16x32_bf16 v[20:23], v[176:179], v[160:163], v[20:23]
	v_mfma_f32_16x16x32_bf16 v[16:19], v[184:187], v[160:163], v[16:19]
	v_mfma_f32_16x16x32_bf16 v[4:7], v[176:179], v[168:171], v[4:7]
	v_mfma_f32_16x16x32_bf16 v[0:3], v[184:187], v[168:171], v[0:3]
	v_mfma_f32_16x16x32_bf16 v[52:55], v[180:183], v[148:151], v[52:55]
	v_mfma_f32_16x16x32_bf16 v[48:51], v[188:191], v[148:151], v[48:51]
	v_mfma_f32_16x16x32_bf16 v[36:39], v[180:183], v[156:159], v[36:39]
	v_mfma_f32_16x16x32_bf16 v[32:35], v[188:191], v[156:159], v[32:35]
	v_mfma_f32_16x16x32_bf16 v[20:23], v[180:183], v[164:167], v[20:23]
	v_mfma_f32_16x16x32_bf16 v[16:19], v[188:191], v[164:167], v[16:19]
	v_mfma_f32_16x16x32_bf16 v[4:7], v[180:183], v[172:175], v[4:7]
	v_mfma_f32_16x16x32_bf16 v[0:3], v[188:191], v[172:175], v[0:3]
	s_setprio 0
	s_add_i32 s45, s45, 2
	s_add_u32 s33, s33, 0x100
	s_addc_u32 s44, s44, 0
	s_cmp_gt_u32 s45, 41
	s_mov_b64 s[20:21], s[22:23]
	s_barrier
	s_cbranch_scc0 .LBB0_1623
	v_mov_b32_e32 v128, v252
	s_lshl_b32 s1, s1, 8
	v_readfirstlane_b32 s20, v128
	s_ashr_i32 s21, s20, 2
	s_andn2_b32 s21, s21, 63
	s_add_i32 s21, s21, s1
	s_lshr_b32 s1, s20, 1
	s_and_b32 s1, s1, 0x60
	s_lshl_b32 s0, s0, 8
	v_and_or_b32 v244, v128, 15, s21
	v_lshrrev_b32_e32 v128, 1, v128
	s_or_b32 s0, s1, s0
	v_and_b32_e32 v129, 64, v195
	v_and_or_b32 v216, v128, 24, s0
	v_xor_b32_e32 v128, 16, v195
	v_add_u32_e32 v129, 64, v129
	v_cmp_lt_i32_e32 vcc, v128, v129
	v_ashrrev_i32_e32 v245, 31, v244
	v_lshlrev_b64 v[220:221], 10, v[244:245]
	v_cndmask_b32_e32 v128, v195, v128, vcc
	v_lshlrev_b32_e32 v200, 2, v128
	v_xor_b32_e32 v128, 32, v195
	v_cmp_lt_i32_e32 vcc, v128, v129
	v_ashrrev_i32_e32 v217, 31, v216
	v_or_b32_e32 v218, 0x80, v216
	v_cndmask_b32_e32 v128, v195, v128, vcc
	v_lshlrev_b32_e32 v199, 2, v128
	v_lshl_add_u64 v[128:129], v[220:221], 0, v[216:217]
	v_lshlrev_b64 v[128:129], 1, v[128:129]
	v_lshl_add_u64 v[240:241], s[18:19], 0, v[128:129]
	v_lshl_add_u64 v[246:247], s[10:11], 0, v[128:129]
	global_load_dwordx4 v[188:191], v[240:241], off
	global_load_dwordx4 v[180:183], v[240:241], off offset:256
	global_load_dwordx4 v[184:187], v[246:247], off
	v_ashrrev_i32_e32 v219, 31, v218
	v_lshl_add_u64 v[128:129], v[220:221], 0, v[218:219]
	v_lshl_add_u64 v[242:243], v[128:129], 1, s[10:11]
	v_or_b32_e32 v128, 16, v244
	v_ashrrev_i32_e32 v129, 31, v128
	v_lshlrev_b64 v[128:129], 10, v[128:129]
	v_lshl_add_u64 v[130:131], v[128:129], 0, v[216:217]
	v_lshl_add_u64 v[128:129], v[128:129], 0, v[218:219]
	v_lshl_add_u64 v[236:237], v[128:129], 1, s[10:11]
	v_or_b32_e32 v128, 32, v244
	v_ashrrev_i32_e32 v129, 31, v128
	v_lshlrev_b64 v[130:131], 1, v[130:131]
	v_lshlrev_b64 v[128:129], 10, v[128:129]
	v_lshl_add_u64 v[234:235], s[18:19], 0, v[130:131]
	v_lshl_add_u64 v[238:239], s[10:11], 0, v[130:131]
	v_lshl_add_u64 v[130:131], v[128:129], 0, v[216:217]
	v_lshl_add_u64 v[128:129], v[128:129], 0, v[218:219]
	v_lshl_add_u64 v[230:231], v[128:129], 1, s[10:11]
	v_or_b32_e32 v128, 48, v244
	v_ashrrev_i32_e32 v129, 31, v128
	v_lshlrev_b64 v[130:131], 1, v[130:131]
	v_lshlrev_b64 v[128:129], 10, v[128:129]
	v_lshl_add_u64 v[226:227], s[18:19], 0, v[130:131]
	v_lshl_add_u64 v[232:233], s[10:11], 0, v[130:131]
	v_lshl_add_u64 v[130:131], v[128:129], 0, v[216:217]
	v_lshlrev_b64 v[130:131], 1, v[130:131]
	v_lshl_add_u64 v[132:133], v[128:129], 0, v[218:219]
	v_lshl_add_u64 v[222:223], s[18:19], 0, v[130:131]
	v_lshl_add_u64 v[228:229], s[10:11], 0, v[130:131]
	v_lshl_add_u64 v[224:225], v[132:133], 1, s[10:11]
	global_load_dwordx4 v[176:179], v[242:243], off
	global_load_dwordx4 v[172:175], v[234:235], off
	global_load_dwordx4 v[164:167], v[234:235], off offset:256
	global_load_dwordx4 v[168:171], v[238:239], off
	global_load_dwordx4 v[160:163], v[236:237], off
	global_load_dwordx4 v[156:159], v[226:227], off
	global_load_dwordx4 v[132:135], v[224:225], off
	global_load_dwordx4 v[152:155], v[232:233], off
	global_load_dwordx4 v[144:147], v[230:231], off
	global_load_dwordx4 v[148:151], v[226:227], off offset:256
	global_load_dwordx4 v[136:139], v[228:229], off
	global_load_dwordx4 v[140:143], v[222:223], off
	global_load_dwordx4 v[128:131], v[222:223], off offset:256
	v_cmp_gt_u32_e32 vcc, 16, v195
	s_waitcnt vmcnt(0)
	v_lshlrev_b32_e32 v248, 16, v188
	v_and_b32_e32 v249, 0xffff0000, v188
	v_lshlrev_b32_e32 v250, 16, v184
	v_and_b32_e32 v251, 0xffff0000, v184
	v_lshlrev_b32_e32 v188, 16, v189
	v_and_b32_e32 v189, 0xffff0000, v189
	v_lshlrev_b32_e32 v184, 16, v185
	v_and_b32_e32 v185, 0xffff0000, v185
	v_pk_add_f32 v[248:249], v[248:249], v[250:251]
	v_pk_add_f32 v[184:185], v[188:189], v[184:185]
	v_pk_fma_f32 v[188:189], v[124:125], 0.5, v[248:249] op_sel_hi:[1,0,1]
	v_pk_fma_f32 v[184:185], v[126:127], 0.5, v[184:185] op_sel_hi:[1,0,1]
	v_lshlrev_b32_e32 v124, 16, v190
	v_and_b32_e32 v125, 0xffff0000, v190
	v_lshlrev_b32_e32 v126, 16, v186
	v_and_b32_e32 v127, 0xffff0000, v186
	v_pk_add_f32 v[124:125], v[124:125], v[126:127]
	v_lshlrev_b32_e32 v126, 16, v191
	v_and_b32_e32 v127, 0xffff0000, v191
	v_lshlrev_b32_e32 v186, 16, v187
	v_and_b32_e32 v187, 0xffff0000, v187
	v_pk_add_f32 v[126:127], v[126:127], v[186:187]
	v_pk_fma_f32 v[190:191], v[120:121], 0.5, v[124:125] op_sel_hi:[1,0,1]
	v_cvt_pk_bf16_f32 v120, v188, v189
	v_pk_fma_f32 v[186:187], v[122:123], 0.5, v[126:127] op_sel_hi:[1,0,1]
	v_and_b32_e32 v123, 0xffff0000, v120
	v_lshlrev_b32_e32 v122, 16, v120
	v_pk_add_f32 v[122:123], v[188:189], v[122:123] neg_lo:[0,1] neg_hi:[0,1]
	v_cvt_pk_bf16_f32 v121, v184, v185
	v_cvt_pk_bf16_f32 v124, v122, v123
	v_and_b32_e32 v123, 0xffff0000, v121
	v_lshlrev_b32_e32 v122, 16, v121
	v_pk_add_f32 v[122:123], v[184:185], v[122:123] neg_lo:[0,1] neg_hi:[0,1]
	s_nop 0
	v_cvt_pk_bf16_f32 v125, v122, v123
	v_cvt_pk_bf16_f32 v122, v190, v191
	v_cvt_pk_bf16_f32 v123, v186, v187
	v_and_b32_e32 v127, 0xffff0000, v122
	v_lshlrev_b32_e32 v126, 16, v122
	v_and_b32_e32 v249, 0xffff0000, v123
	v_lshlrev_b32_e32 v248, 16, v123
	v_pk_add_f32 v[126:127], v[190:191], v[126:127] neg_lo:[0,1] neg_hi:[0,1]
	v_pk_add_f32 v[248:249], v[186:187], v[248:249] neg_lo:[0,1] neg_hi:[0,1]
	v_cvt_pk_bf16_f32 v126, v126, v127
	v_cvt_pk_bf16_f32 v127, v248, v249
	global_store_dwordx4 v[240:241], v[120:123], off
	global_store_dwordx4 v[246:247], v[124:127], off
	s_nop 0
	v_pk_mul_f32 v[122:123], v[190:191], v[190:191]
	v_pk_mul_f32 v[120:121], v[186:187], v[186:187]
	v_pk_fma_f32 v[122:123], v[188:189], v[188:189], v[122:123]
	v_pk_fma_f32 v[120:121], v[184:185], v[184:185], v[120:121]
	v_add_f32_e32 v122, v122, v123
	v_add_f32_e32 v120, v120, v122
	v_add_f32_e32 v120, v121, v120
	ds_bpermute_b32 v121, v200, v120
	v_lshl_add_u64 v[184:185], v[244:245], 2, s[14:15]
	s_waitcnt lgkmcnt(0)
	v_add_f32_e32 v120, v120, v121
	ds_bpermute_b32 v121, v199, v120
	s_and_saveexec_b64 s[20:21], vcc
	s_cbranch_execz .LBB0_1626
	s_waitcnt lgkmcnt(0)
	v_add_f32_e32 v120, v120, v121
	global_atomic_add_f32 v[184:185], v120, off

.LBB0_2803:
	v_mov_b64_e32 v[0:1], 0x580
	s_ashr_i32 s9, s8, 31
	v_cmp_lt_i64_e32 vcc, s[12:13], v[0:1]
	s_lshl_b64 s[12:13], s[8:9], 19
	s_add_u32 s12, s82, s12
	s_addc_u32 s13, s83, s13
	s_and_b64 s[14:15], vcc, exec
	s_cselect_b32 s9, s13, s21
	s_cselect_b32 s33, s12, s20
	s_ashr_i32 s11, s10, 31
	s_lshl_b64 s[14:15], s[10:11], 19
	s_add_u32 s14, s26, s14
	s_addc_u32 s15, s27, s15
	s_and_b64 s[22:23], vcc, exec
	s_cselect_b32 s11, s15, s19
	s_cselect_b32 s38, s14, s18
	s_add_u32 s39, s18, 0x100
	s_addc_u32 s40, s19, 0
	s_add_u32 s18, s20, 0x40080
	v_mov_b32_e32 v0, 0
	s_addc_u32 s19, s21, 0
	s_mov_b32 s41, -2
	v_mov_b32_e32 v1, v0
	v_mov_b32_e32 v2, v0
	v_mov_b32_e32 v3, v0
	v_mov_b32_e32 v8, v0
	v_mov_b32_e32 v9, v0
	v_mov_b32_e32 v10, v0
	v_mov_b32_e32 v11, v0
	v_mov_b32_e32 v16, v0
	v_mov_b32_e32 v17, v0
	v_mov_b32_e32 v18, v0
	v_mov_b32_e32 v19, v0
	v_mov_b32_e32 v24, v0
	v_mov_b32_e32 v25, v0
	v_mov_b32_e32 v26, v0
	v_mov_b32_e32 v27, v0
	v_mov_b32_e32 v32, v0
	v_mov_b32_e32 v33, v0
	v_mov_b32_e32 v34, v0
	v_mov_b32_e32 v35, v0
	v_mov_b32_e32 v40, v0
	v_mov_b32_e32 v41, v0
	v_mov_b32_e32 v42, v0
	v_mov_b32_e32 v43, v0
	v_mov_b32_e32 v48, v0
	v_mov_b32_e32 v49, v0
	v_mov_b32_e32 v50, v0
	v_mov_b32_e32 v51, v0
	v_mov_b32_e32 v56, v0
	v_mov_b32_e32 v57, v0
	v_mov_b32_e32 v58, v0
	v_mov_b32_e32 v59, v0
	v_mov_b32_e32 v4, v0
	v_mov_b32_e32 v5, v0
	v_mov_b32_e32 v6, v0
	v_mov_b32_e32 v7, v0
	v_mov_b32_e32 v12, v0
	v_mov_b32_e32 v13, v0
	v_mov_b32_e32 v14, v0
	v_mov_b32_e32 v15, v0
	v_mov_b32_e32 v20, v0
	v_mov_b32_e32 v21, v0
	v_mov_b32_e32 v22, v0
	v_mov_b32_e32 v23, v0
	v_mov_b32_e32 v28, v0
	v_mov_b32_e32 v29, v0
	v_mov_b32_e32 v30, v0
	v_mov_b32_e32 v31, v0
	v_mov_b32_e32 v36, v0
	v_mov_b32_e32 v37, v0
	v_mov_b32_e32 v38, v0
	v_mov_b32_e32 v39, v0
	v_mov_b32_e32 v44, v0
	v_mov_b32_e32 v45, v0
	v_mov_b32_e32 v46, v0
	v_mov_b32_e32 v47, v0
	v_mov_b32_e32 v52, v0
	v_mov_b32_e32 v53, v0
	v_mov_b32_e32 v54, v0
	v_mov_b32_e32 v55, v0
	v_mov_b32_e32 v60, v0
	v_mov_b32_e32 v61, v0
	v_mov_b32_e32 v62, v0
	v_mov_b32_e32 v63, v0
	s_waitcnt vmcnt(0)
	v_mov_b32_e32 v64, v0
	v_mov_b32_e32 v65, v0
	v_mov_b32_e32 v66, v0
	v_mov_b32_e32 v67, v0
	v_mov_b32_e32 v72, v0
	v_mov_b32_e32 v73, v0
	v_mov_b32_e32 v74, v0
	v_mov_b32_e32 v75, v0
	v_mov_b32_e32 v80, v0
	v_mov_b32_e32 v81, v0
	v_mov_b32_e32 v82, v0
	v_mov_b32_e32 v83, v0
	v_mov_b32_e32 v88, v0
	v_mov_b32_e32 v89, v0
	v_mov_b32_e32 v90, v0
	v_mov_b32_e32 v91, v0
	v_mov_b32_e32 v96, v0
	v_mov_b32_e32 v97, v0
	v_mov_b32_e32 v98, v0
	v_mov_b32_e32 v99, v0
	v_mov_b32_e32 v104, v0
	v_mov_b32_e32 v105, v0
	v_mov_b32_e32 v106, v0
	v_mov_b32_e32 v107, v0
	v_mov_b32_e32 v112, v0
	v_mov_b32_e32 v113, v0
	v_mov_b32_e32 v114, v0
	v_mov_b32_e32 v115, v0
	v_mov_b32_e32 v120, v0
	v_mov_b32_e32 v121, v0
	v_mov_b32_e32 v122, v0
	v_mov_b32_e32 v123, v0
	v_mov_b32_e32 v68, v0
	v_mov_b32_e32 v69, v0
	v_mov_b32_e32 v70, v0
	v_mov_b32_e32 v71, v0
	v_mov_b32_e32 v76, v0
	v_mov_b32_e32 v77, v0
	v_mov_b32_e32 v78, v0
	v_mov_b32_e32 v79, v0
	v_mov_b32_e32 v84, v0
	v_mov_b32_e32 v85, v0
	v_mov_b32_e32 v86, v0
	v_mov_b32_e32 v87, v0
	v_mov_b32_e32 v92, v0
	v_mov_b32_e32 v93, v0
	v_mov_b32_e32 v94, v0
	v_mov_b32_e32 v95, v0
	v_mov_b32_e32 v100, v0
	v_mov_b32_e32 v101, v0
	v_mov_b32_e32 v102, v0
	v_mov_b32_e32 v103, v0
	v_mov_b32_e32 v108, v0
	v_mov_b32_e32 v109, v0
	v_mov_b32_e32 v110, v0
	v_mov_b32_e32 v111, v0
	v_mov_b32_e32 v116, v0
	v_mov_b32_e32 v117, v0
	v_mov_b32_e32 v118, v0
	v_mov_b32_e32 v119, v0
	v_mov_b32_e32 v124, v0
	v_mov_b32_e32 v125, v0
	v_mov_b32_e32 v126, v0
	v_mov_b32_e32 v127, v0
	v_add_u32_e32 v202, 0x10000, v151
	v_add_u32_e32 v203, 0x14000, v151
	v_add_u32_e32 v204, 0x18000, v151
	v_add_u32_e32 v205, 0x1c000, v151
.LBB0_2804:
	s_add_u32 s20, s18, 0xfffc0080
	s_addc_u32 s21, s19, -1
	s_add_i32 s42, 0, 0x10000
	ds_read_b128 v[138:141], v202
	ds_read_b128 v[142:145], v202 offset:1024
	ds_read_b128 v[146:149], v202 offset:2048
	ds_read_b128 v[154:157], v202 offset:3072
	s_cmp_eq_u32 s41, 12
	s_cselect_b32 s23, s9, s21
	s_cselect_b32 s22, s33, s20
	s_cselect_b32 s21, s11, s40
	s_cselect_b32 s20, s38, s39
	s_add_i32 m0, s17, 0xc000
	ds_read_b128 v[158:161], v152
	ds_read_b128 v[162:165], v152 offset:1024
	ds_read_b128 v[166:169], v152 offset:2048
	ds_read_b128 v[170:173], v152 offset:3072
	ds_read_b128 v[174:177], v152 offset:4096
	ds_read_b128 v[178:181], v152 offset:5120
	ds_read_b128 v[182:185], v152 offset:6144
	ds_read_b128 v[186:189], v152 offset:7168
	global_load_lds_dwordx4 v136, s[18:19]
	s_add_i32 m0, s17, 0xe000
	s_nop 0
	global_load_lds_dwordx4 v134, s[18:19]
	s_waitcnt lgkmcnt(8)
	s_barrier
	s_waitcnt lgkmcnt(0)
	s_setprio 1
	s_waitcnt lgkmcnt(0)
	v_mfma_f32_16x16x32_bf16 v[124:127], v[138:141], v[158:161], v[124:127]
	v_mfma_f32_16x16x32_bf16 v[116:119], v[146:149], v[158:161], v[116:119]
	v_mfma_f32_16x16x32_bf16 v[108:111], v[138:141], v[166:169], v[108:111]
	v_mfma_f32_16x16x32_bf16 v[100:103], v[146:149], v[166:169], v[100:103]
	v_mfma_f32_16x16x32_bf16 v[92:95], v[138:141], v[174:177], v[92:95]
	v_mfma_f32_16x16x32_bf16 v[84:87], v[146:149], v[174:177], v[84:87]
	v_mfma_f32_16x16x32_bf16 v[76:79], v[138:141], v[182:185], v[76:79]
	v_mfma_f32_16x16x32_bf16 v[68:71], v[146:149], v[182:185], v[68:71]
	v_mfma_f32_16x16x32_bf16 v[124:127], v[142:145], v[162:165], v[124:127]
	v_mfma_f32_16x16x32_bf16 v[116:119], v[154:157], v[162:165], v[116:119]
	v_mfma_f32_16x16x32_bf16 v[108:111], v[142:145], v[170:173], v[108:111]
	v_mfma_f32_16x16x32_bf16 v[100:103], v[154:157], v[170:173], v[100:103]
	v_mfma_f32_16x16x32_bf16 v[92:95], v[142:145], v[178:181], v[92:95]
	v_mfma_f32_16x16x32_bf16 v[84:87], v[154:157], v[178:181], v[84:87]
	v_mfma_f32_16x16x32_bf16 v[76:79], v[142:145], v[186:189], v[76:79]
	v_mfma_f32_16x16x32_bf16 v[68:71], v[154:157], v[186:189], v[68:71]
	s_setprio 0
	s_barrier
	s_add_i32 s44, 0, 0x14000
	s_add_i32 s42, s42, s28
	s_mov_b32 m0, s42
	ds_read_b128 v[198:201], v203
	ds_read_b128 v[206:209], v203 offset:1024
	ds_read_b128 v[210:213], v203 offset:2048
	ds_read_b128 v[214:217], v203 offset:3072
	global_load_lds_dwordx4 v192, s[20:21]
	s_add_i32 m0, s42, 0x2000
	s_nop 0
	global_load_lds_dwordx4 v128, s[20:21]
	s_barrier
	s_waitcnt lgkmcnt(0)
	s_setprio 1
	s_waitcnt lgkmcnt(0)
	v_mfma_f32_16x16x32_bf16 v[120:123], v[198:201], v[158:161], v[120:123]
	v_mfma_f32_16x16x32_bf16 v[112:115], v[210:213], v[158:161], v[112:115]
	v_mfma_f32_16x16x32_bf16 v[104:107], v[198:201], v[166:169], v[104:107]
	v_mfma_f32_16x16x32_bf16 v[96:99], v[210:213], v[166:169], v[96:99]
	v_mfma_f32_16x16x32_bf16 v[88:91], v[198:201], v[174:177], v[88:91]
	v_mfma_f32_16x16x32_bf16 v[80:83], v[210:213], v[174:177], v[80:83]
	v_mfma_f32_16x16x32_bf16 v[72:75], v[198:201], v[182:185], v[72:75]
	v_mfma_f32_16x16x32_bf16 v[64:67], v[210:213], v[182:185], v[64:67]
	v_mfma_f32_16x16x32_bf16 v[120:123], v[206:209], v[162:165], v[120:123]
	v_mfma_f32_16x16x32_bf16 v[112:115], v[214:217], v[162:165], v[112:115]
	v_mfma_f32_16x16x32_bf16 v[104:107], v[206:209], v[170:173], v[104:107]
	v_mfma_f32_16x16x32_bf16 v[96:99], v[214:217], v[170:173], v[96:99]
	v_mfma_f32_16x16x32_bf16 v[88:91], v[206:209], v[178:181], v[88:91]
	v_mfma_f32_16x16x32_bf16 v[80:83], v[214:217], v[178:181], v[80:83]
	v_mfma_f32_16x16x32_bf16 v[72:75], v[206:209], v[186:189], v[72:75]
	v_mfma_f32_16x16x32_bf16 v[64:67], v[214:217], v[186:189], v[64:67]
	s_setprio 0
	s_mov_b32 m0, s17
	s_add_u32 vcc_lo, s22, 0x80
	s_addc_u32 vcc_hi, s23, 0
	s_barrier
	ds_read_b128 v[158:161], v152 offset:16384
	ds_read_b128 v[162:165], v152 offset:17408
	ds_read_b128 v[166:169], v152 offset:18432
	ds_read_b128 v[170:173], v152 offset:19456
	ds_read_b128 v[174:177], v152 offset:20480
	ds_read_b128 v[178:181], v152 offset:21504
	ds_read_b128 v[182:185], v152 offset:22528
	ds_read_b128 v[186:189], v152 offset:23552
	global_load_lds_dwordx4 v132, s[22:23]
	s_mov_b32 m0, s29
	s_nop 0
	global_load_lds_dwordx4 v130, s[22:23]
	s_barrier
	s_waitcnt lgkmcnt(0)
	s_setprio 1
	s_waitcnt lgkmcnt(0)
	v_mfma_f32_16x16x32_bf16 v[60:63], v[138:141], v[158:161], v[60:63]
	v_mfma_f32_16x16x32_bf16 v[52:55], v[146:149], v[158:161], v[52:55]
	v_mfma_f32_16x16x32_bf16 v[44:47], v[138:141], v[166:169], v[44:47]
	v_mfma_f32_16x16x32_bf16 v[36:39], v[146:149], v[166:169], v[36:39]
	v_mfma_f32_16x16x32_bf16 v[28:31], v[138:141], v[174:177], v[28:31]
	v_mfma_f32_16x16x32_bf16 v[20:23], v[146:149], v[174:177], v[20:23]
	v_mfma_f32_16x16x32_bf16 v[12:15], v[138:141], v[182:185], v[12:15]
	v_mfma_f32_16x16x32_bf16 v[4:7], v[146:149], v[182:185], v[4:7]
	v_mfma_f32_16x16x32_bf16 v[60:63], v[142:145], v[162:165], v[60:63]
	v_mfma_f32_16x16x32_bf16 v[52:55], v[154:157], v[162:165], v[52:55]
	v_mfma_f32_16x16x32_bf16 v[44:47], v[142:145], v[170:173], v[44:47]
	v_mfma_f32_16x16x32_bf16 v[36:39], v[154:157], v[170:173], v[36:39]
	v_mfma_f32_16x16x32_bf16 v[28:31], v[142:145], v[178:181], v[28:31]
	v_mfma_f32_16x16x32_bf16 v[20:23], v[154:157], v[178:181], v[20:23]
	v_mfma_f32_16x16x32_bf16 v[12:15], v[142:145], v[186:189], v[12:15]
	v_mfma_f32_16x16x32_bf16 v[4:7], v[154:157], v[186:189], v[4:7]
	s_setprio 0
	s_barrier
	s_add_u32 s42, s20, 0x40000
	s_addc_u32 s43, s21, 0
	s_add_i32 s44, s44, s28
	s_mov_b32 m0, s44
	s_nop 0
	global_load_lds_dwordx4 v192, s[42:43]
	s_add_i32 m0, s44, 0x2000
	s_nop 0
	global_load_lds_dwordx4 v128, s[42:43]
	s_waitcnt vmcnt(6)
	s_barrier
	s_setprio 1
	v_mfma_f32_16x16x32_bf16 v[56:59], v[198:201], v[158:161], v[56:59]
	v_mfma_f32_16x16x32_bf16 v[48:51], v[210:213], v[158:161], v[48:51]
	v_mfma_f32_16x16x32_bf16 v[40:43], v[198:201], v[166:169], v[40:43]
	v_mfma_f32_16x16x32_bf16 v[32:35], v[210:213], v[166:169], v[32:35]
	v_mfma_f32_16x16x32_bf16 v[24:27], v[198:201], v[174:177], v[24:27]
	v_mfma_f32_16x16x32_bf16 v[16:19], v[210:213], v[174:177], v[16:19]
	v_mfma_f32_16x16x32_bf16 v[8:11], v[198:201], v[182:185], v[8:11]
	v_mfma_f32_16x16x32_bf16 v[0:3], v[210:213], v[182:185], v[0:3]
	v_mfma_f32_16x16x32_bf16 v[56:59], v[206:209], v[162:165], v[56:59]
	v_mfma_f32_16x16x32_bf16 v[48:51], v[214:217], v[162:165], v[48:51]
	v_mfma_f32_16x16x32_bf16 v[40:43], v[206:209], v[170:173], v[40:43]
	v_mfma_f32_16x16x32_bf16 v[32:35], v[214:217], v[170:173], v[32:35]
	v_mfma_f32_16x16x32_bf16 v[24:27], v[206:209], v[178:181], v[24:27]
	v_mfma_f32_16x16x32_bf16 v[16:19], v[214:217], v[178:181], v[16:19]
	v_mfma_f32_16x16x32_bf16 v[8:11], v[206:209], v[186:189], v[8:11]
	v_mfma_f32_16x16x32_bf16 v[0:3], v[214:217], v[186:189], v[0:3]
	s_setprio 0
	s_add_i32 s42, 0, 0x18000
	s_barrier
	ds_read_b128 v[138:141], v204
	ds_read_b128 v[142:145], v204 offset:1024
	ds_read_b128 v[146:149], v204 offset:2048
	ds_read_b128 v[154:157], v204 offset:3072
	s_add_u32 s22, s22, 0x40000
	s_addc_u32 s23, s23, 0
	s_mov_b32 m0, s30
	ds_read_b128 v[158:161], v152 offset:32768
	ds_read_b128 v[162:165], v152 offset:33792
	ds_read_b128 v[166:169], v152 offset:34816
	ds_read_b128 v[170:173], v152 offset:35840
	ds_read_b128 v[174:177], v152 offset:36864
	ds_read_b128 v[178:181], v152 offset:37888
	ds_read_b128 v[182:185], v152 offset:38912
	ds_read_b128 v[186:189], v152 offset:39936
	global_load_lds_dwordx4 v132, s[22:23]
	s_mov_b32 m0, s31
	s_nop 0
	global_load_lds_dwordx4 v130, s[22:23]
	s_waitcnt lgkmcnt(8)
	s_barrier
	s_waitcnt lgkmcnt(0)
	s_setprio 1
	s_waitcnt lgkmcnt(0)
	v_mfma_f32_16x16x32_bf16 v[124:127], v[138:141], v[158:161], v[124:127]
	v_mfma_f32_16x16x32_bf16 v[116:119], v[146:149], v[158:161], v[116:119]
	v_mfma_f32_16x16x32_bf16 v[108:111], v[138:141], v[166:169], v[108:111]
	v_mfma_f32_16x16x32_bf16 v[100:103], v[146:149], v[166:169], v[100:103]
	v_mfma_f32_16x16x32_bf16 v[92:95], v[138:141], v[174:177], v[92:95]
	v_mfma_f32_16x16x32_bf16 v[84:87], v[146:149], v[174:177], v[84:87]
	v_mfma_f32_16x16x32_bf16 v[76:79], v[138:141], v[182:185], v[76:79]
	v_mfma_f32_16x16x32_bf16 v[68:71], v[146:149], v[182:185], v[68:71]
	v_mfma_f32_16x16x32_bf16 v[124:127], v[142:145], v[162:165], v[124:127]
	v_mfma_f32_16x16x32_bf16 v[116:119], v[154:157], v[162:165], v[116:119]
	v_mfma_f32_16x16x32_bf16 v[108:111], v[142:145], v[170:173], v[108:111]
	v_mfma_f32_16x16x32_bf16 v[100:103], v[154:157], v[170:173], v[100:103]
	v_mfma_f32_16x16x32_bf16 v[92:95], v[142:145], v[178:181], v[92:95]
	v_mfma_f32_16x16x32_bf16 v[84:87], v[154:157], v[178:181], v[84:87]
	v_mfma_f32_16x16x32_bf16 v[76:79], v[142:145], v[186:189], v[76:79]
	v_mfma_f32_16x16x32_bf16 v[68:71], v[154:157], v[186:189], v[68:71]
	s_setprio 0
	s_barrier
	s_add_i32 s22, 0, 0x1c000
	s_add_i32 s23, s42, s28
	s_add_u32 s100, s20, 0x80
	s_addc_u32 s101, s21, 0
	s_mov_b32 m0, s23
	ds_read_b128 v[198:201], v205
	ds_read_b128 v[206:209], v205 offset:1024
	ds_read_b128 v[210:213], v205 offset:2048
	ds_read_b128 v[214:217], v205 offset:3072
	global_load_lds_dwordx4 v192, s[100:101]
	s_add_i32 m0, s23, 0x2000
	s_nop 0
	global_load_lds_dwordx4 v128, s[100:101]
	s_barrier
	s_waitcnt lgkmcnt(0)
	s_setprio 1
	s_waitcnt lgkmcnt(0)
	v_mfma_f32_16x16x32_bf16 v[120:123], v[198:201], v[158:161], v[120:123]
	v_mfma_f32_16x16x32_bf16 v[112:115], v[210:213], v[158:161], v[112:115]
	v_mfma_f32_16x16x32_bf16 v[104:107], v[198:201], v[166:169], v[104:107]
	v_mfma_f32_16x16x32_bf16 v[96:99], v[210:213], v[166:169], v[96:99]
	v_mfma_f32_16x16x32_bf16 v[88:91], v[198:201], v[174:177], v[88:91]
	v_mfma_f32_16x16x32_bf16 v[80:83], v[210:213], v[174:177], v[80:83]
	v_mfma_f32_16x16x32_bf16 v[72:75], v[198:201], v[182:185], v[72:75]
	v_mfma_f32_16x16x32_bf16 v[64:67], v[210:213], v[182:185], v[64:67]
	v_mfma_f32_16x16x32_bf16 v[120:123], v[206:209], v[162:165], v[120:123]
	v_mfma_f32_16x16x32_bf16 v[112:115], v[214:217], v[162:165], v[112:115]
	v_mfma_f32_16x16x32_bf16 v[104:107], v[206:209], v[170:173], v[104:107]
	v_mfma_f32_16x16x32_bf16 v[96:99], v[214:217], v[170:173], v[96:99]
	v_mfma_f32_16x16x32_bf16 v[88:91], v[206:209], v[178:181], v[88:91]
	v_mfma_f32_16x16x32_bf16 v[80:83], v[214:217], v[178:181], v[80:83]
	v_mfma_f32_16x16x32_bf16 v[72:75], v[206:209], v[186:189], v[72:75]
	v_mfma_f32_16x16x32_bf16 v[64:67], v[214:217], v[186:189], v[64:67]
	s_setprio 0
	s_mov_b32 m0, s34
	s_barrier
	ds_read_b128 v[158:161], v152 offset:49152
	ds_read_b128 v[162:165], v152 offset:50176
	ds_read_b128 v[166:169], v152 offset:51200
	ds_read_b128 v[170:173], v152 offset:52224
	ds_read_b128 v[174:177], v152 offset:53248
	ds_read_b128 v[178:181], v152 offset:54272
	ds_read_b128 v[182:185], v152 offset:55296
	ds_read_b128 v[186:189], v152 offset:56320
	global_load_lds_dwordx4 v132, vcc
	s_mov_b32 m0, s35
	s_nop 0
	global_load_lds_dwordx4 v130, vcc
	s_barrier
	s_waitcnt lgkmcnt(0)
	s_setprio 1
	s_waitcnt lgkmcnt(0)
	v_mfma_f32_16x16x32_bf16 v[60:63], v[138:141], v[158:161], v[60:63]
	v_mfma_f32_16x16x32_bf16 v[52:55], v[146:149], v[158:161], v[52:55]
	v_mfma_f32_16x16x32_bf16 v[44:47], v[138:141], v[166:169], v[44:47]
	v_mfma_f32_16x16x32_bf16 v[36:39], v[146:149], v[166:169], v[36:39]
	v_mfma_f32_16x16x32_bf16 v[28:31], v[138:141], v[174:177], v[28:31]
	v_mfma_f32_16x16x32_bf16 v[20:23], v[146:149], v[174:177], v[20:23]
	v_mfma_f32_16x16x32_bf16 v[12:15], v[138:141], v[182:185], v[12:15]
	v_mfma_f32_16x16x32_bf16 v[4:7], v[146:149], v[182:185], v[4:7]
	v_mfma_f32_16x16x32_bf16 v[60:63], v[142:145], v[162:165], v[60:63]
	v_mfma_f32_16x16x32_bf16 v[52:55], v[154:157], v[162:165], v[52:55]
	v_mfma_f32_16x16x32_bf16 v[44:47], v[142:145], v[170:173], v[44:47]
	v_mfma_f32_16x16x32_bf16 v[36:39], v[154:157], v[170:173], v[36:39]
	v_mfma_f32_16x16x32_bf16 v[28:31], v[142:145], v[178:181], v[28:31]
	v_mfma_f32_16x16x32_bf16 v[20:23], v[154:157], v[178:181], v[20:23]
	v_mfma_f32_16x16x32_bf16 v[12:15], v[142:145], v[186:189], v[12:15]
	v_mfma_f32_16x16x32_bf16 v[4:7], v[154:157], v[186:189], v[4:7]
	s_setprio 0
	s_barrier
	s_add_u32 s20, s20, 0x40080
	s_addc_u32 s21, s21, 0
	s_add_i32 s22, s22, s28
	s_mov_b32 m0, s22
	s_nop 0
	global_load_lds_dwordx4 v192, s[20:21]
	s_add_i32 m0, s22, 0x2000
	s_nop 0
	global_load_lds_dwordx4 v128, s[20:21]
	s_waitcnt vmcnt(6)
	s_barrier
	s_setprio 1
	v_mfma_f32_16x16x32_bf16 v[56:59], v[198:201], v[158:161], v[56:59]
	v_mfma_f32_16x16x32_bf16 v[48:51], v[210:213], v[158:161], v[48:51]
	v_mfma_f32_16x16x32_bf16 v[40:43], v[198:201], v[166:169], v[40:43]
	v_mfma_f32_16x16x32_bf16 v[32:35], v[210:213], v[166:169], v[32:35]
	v_mfma_f32_16x16x32_bf16 v[24:27], v[198:201], v[174:177], v[24:27]
	v_mfma_f32_16x16x32_bf16 v[16:19], v[210:213], v[174:177], v[16:19]
	v_mfma_f32_16x16x32_bf16 v[8:11], v[198:201], v[182:185], v[8:11]
	v_mfma_f32_16x16x32_bf16 v[0:3], v[210:213], v[182:185], v[0:3]
	v_mfma_f32_16x16x32_bf16 v[56:59], v[206:209], v[162:165], v[56:59]
	v_mfma_f32_16x16x32_bf16 v[48:51], v[214:217], v[162:165], v[48:51]
	v_mfma_f32_16x16x32_bf16 v[40:43], v[206:209], v[170:173], v[40:43]
	v_mfma_f32_16x16x32_bf16 v[32:35], v[214:217], v[170:173], v[32:35]
	v_mfma_f32_16x16x32_bf16 v[24:27], v[206:209], v[178:181], v[24:27]
	v_mfma_f32_16x16x32_bf16 v[16:19], v[214:217], v[178:181], v[16:19]
	v_mfma_f32_16x16x32_bf16 v[8:11], v[206:209], v[186:189], v[8:11]
	v_mfma_f32_16x16x32_bf16 v[0:3], v[214:217], v[186:189], v[0:3]
	s_setprio 0
	s_add_i32 s41, s41, 2
	s_add_u32 s39, s39, 0x100
	s_addc_u32 s40, s40, 0
	s_add_u32 s18, s18, 0x100
	s_addc_u32 s19, s19, 0
	s_cmp_gt_u32 s41, 13
	s_barrier
	s_cbranch_scc0 .LBB0_2804
	v_mov_b32_e32 v139, v252
	s_lshl_b32 s11, s16, 8
	v_readfirstlane_b32 s9, v139
	s_ashr_i32 s16, s9, 2
	s_andn2_b32 s16, s16, 63
	s_lshr_b32 s9, s9, 1
	s_add_i32 s16, s16, s11
	s_lshl_b32 s11, s37, 7
	s_and_b32 s9, s9, 0x60
	v_and_or_b32 v138, v139, 15, s16
	s_or_b32 s9, s9, s11
	v_lshrrev_b32_e32 v139, 1, v139
	v_and_or_b32 v148, v139, 24, s9
	v_ashrrev_i32_e32 v139, 31, v138
	v_lshl_add_u64 v[140:141], v[138:139], 2, s[6:7]
	v_or_b32_e32 v146, 16, v138
	v_ashrrev_i32_e32 v147, 31, v146
	v_lshl_add_u64 v[142:143], v[146:147], 2, s[6:7]
	v_or_b32_e32 v144, 32, v138
	v_ashrrev_i32_e32 v145, 31, v144
	v_lshl_add_u64 v[142:143], v[144:145], 2, s[6:7]
	v_or_b32_e32 v142, 48, v138
	v_ashrrev_i32_e32 v143, 31, v142
	v_lshl_add_u64 v[154:155], v[142:143], 2, s[6:7]
	v_pk_mul_f32 v[120:121], v[124:125], v[120:121]
	v_pk_mul_f32 v[122:123], v[126:127], v[122:123]
	v_pk_mul_f32 v[112:113], v[116:117], v[112:113]
	v_pk_mul_f32 v[114:115], v[118:119], v[114:115]
	v_ashrrev_i32_e32 v149, 31, v148
	s_movk_i32 s9, 0x1600
	v_pk_mul_f32 v[104:105], v[108:109], v[104:105]
	v_pk_mul_f32 v[106:107], v[110:111], v[106:107]
	v_pk_mul_f32 v[96:97], v[100:101], v[96:97]
	v_pk_mul_f32 v[98:99], v[102:103], v[98:99]
	v_pk_mul_f32 v[88:89], v[92:93], v[88:89]
	v_pk_mul_f32 v[90:91], v[94:95], v[90:91]
	v_pk_mul_f32 v[80:81], v[84:85], v[80:81]
	v_pk_mul_f32 v[82:83], v[86:87], v[82:83]
	v_pk_mul_f32 v[72:73], v[76:77], v[72:73]
	v_pk_mul_f32 v[74:75], v[78:79], v[74:75]
	v_pk_mul_f32 v[64:65], v[68:69], v[64:65]
	v_pk_mul_f32 v[66:67], v[70:71], v[66:67]
	v_pk_mul_f32 v[56:57], v[60:61], v[56:57]
	v_pk_mul_f32 v[58:59], v[62:63], v[58:59]
	v_pk_mul_f32 v[48:49], v[52:53], v[48:49]
	v_pk_mul_f32 v[50:51], v[54:55], v[50:51]
	v_pk_mul_f32 v[40:41], v[44:45], v[40:41]
	v_pk_mul_f32 v[42:43], v[46:47], v[42:43]
	v_pk_mul_f32 v[32:33], v[36:37], v[32:33]
	v_pk_mul_f32 v[34:35], v[38:39], v[34:35]
	v_pk_mul_f32 v[24:25], v[28:29], v[24:25]
	v_pk_mul_f32 v[26:27], v[30:31], v[26:27]
	v_pk_mul_f32 v[16:17], v[20:21], v[16:17]
	v_pk_mul_f32 v[18:19], v[22:23], v[18:19]
	v_pk_mul_f32 v[8:9], v[12:13], v[8:9]
	v_pk_mul_f32 v[10:11], v[14:15], v[10:11]
	v_pk_mul_f32 v[0:1], v[4:5], v[0:1]
	v_pk_mul_f32 v[2:3], v[6:7], v[2:3]
	s_mov_b32 s37, s10
	s_mov_b32 s16, s8
	s_mov_b64 s[20:21], s[12:13]
	v_fmamk_f32 v143, v231, 0x3a800000, v194
	v_cmp_gt_f32_e32 vcc, s2, v143
	v_mul_f32_e32 v150, 0x4b800000, v143
	s_nop 0
	v_cndmask_b32_e32 v143, v143, v150, vcc
	v_rsq_f32_e32 v143, v143
	s_nop 0
	v_mul_f32_e32 v150, 0x45800000, v143
	v_cndmask_b32_e32 v143, v143, v150, vcc
	v_mul_f32_e32 v154, 0xbfb8aa3b, v143
	v_pk_mul_f32 v[158:159], v[124:125], v[154:155] op_sel_hi:[1,0]
	v_mul_f32_e32 v150, v143, v143
	v_exp_f32_e32 v143, v158
	v_pk_mul_f32 v[156:157], v[126:127], v[154:155] op_sel_hi:[1,0]
	v_add_f32_e32 v143, 1.0, v143
	v_rcp_f32_e32 v158, v143
	v_exp_f32_e32 v143, v159
	s_nop 0
	v_add_f32_e32 v143, 1.0, v143
	v_rcp_f32_e32 v159, v143
	v_exp_f32_e32 v143, v156
	v_pk_mul_f32 v[124:125], v[150:151], v[158:159] op_sel_hi:[0,1]
	v_add_f32_e32 v143, 1.0, v143
	v_rcp_f32_e32 v156, v143
	v_exp_f32_e32 v143, v157
	v_pk_mul_f32 v[120:121], v[120:121], v[124:125]
	v_add_f32_e32 v143, 1.0, v143
	v_rcp_f32_e32 v157, v143
	v_cvt_pk_bf16_f32 v124, v121, s0
	v_cvt_pk_bf16_f32 v120, v120, s0
	v_pk_mul_f32 v[126:127], v[150:151], v[156:157] op_sel_hi:[0,1]
	v_pk_mul_f32 v[122:123], v[122:123], v[126:127]
	s_nop 0
	v_cvt_pk_bf16_f32 v121, v122, v123
	v_lshlrev_b32_e32 v122, 16, v124
	v_pk_mul_f32 v[124:125], v[116:117], v[154:155] op_sel_hi:[1,0]
	v_or_b32_sdwa v120, v122, v120 dst_sel:DWORD dst_unused:UNUSED_PAD src0_sel:DWORD src1_sel:WORD_0
	v_pk_mul_f32 v[122:123], v[118:119], v[154:155] op_sel_hi:[1,0]
	v_exp_f32_e32 v124, v124
	v_exp_f32_e32 v125, v125
	v_exp_f32_e32 v122, v122
	v_exp_f32_e32 v123, v123
	v_add_f32_e32 v124, 1.0, v124
	v_add_f32_e32 v125, 1.0, v125
	v_rcp_f32_e32 v124, v124
	v_rcp_f32_e32 v125, v125
	v_add_f32_e32 v122, 1.0, v122
	v_add_f32_e32 v123, 1.0, v123
	v_rcp_f32_e32 v122, v122
	v_rcp_f32_e32 v123, v123
	v_pk_mul_f32 v[116:117], v[150:151], v[124:125] op_sel_hi:[0,1]
	v_pk_mul_f32 v[112:113], v[112:113], v[116:117]
	v_pk_mul_f32 v[118:119], v[150:151], v[122:123] op_sel_hi:[0,1]
	v_pk_mul_f32 v[114:115], v[114:115], v[118:119]
	v_cvt_pk_bf16_f32 v122, v112, v113
	v_mov_b64_e32 v[112:113], s[4:5]
	v_cvt_pk_bf16_f32 v123, v114, v115
	v_mad_i64_i32 v[116:117], s[18:19], v138, s9, v[112:113]
	v_lshlrev_b64 v[114:115], 1, v[148:149]
	v_lshl_add_u64 v[116:117], v[116:117], 0, v[114:115]
	global_store_dwordx4 v[116:117], v[120:123], off
	v_fmamk_f32 v116, v232, 0x3a800000, v194
	v_cmp_gt_f32_e32 vcc, s2, v116
	v_mul_f32_e32 v117, 0x4b800000, v116
	s_nop 0
	v_cndmask_b32_e32 v116, v116, v117, vcc
	v_rsq_f32_e32 v116, v116
	s_nop 0
	v_mul_f32_e32 v117, 0x45800000, v116
	v_cndmask_b32_e32 v116, v116, v117, vcc
	v_mul_f32_e32 v118, 0xbfb8aa3b, v116
	v_pk_mul_f32 v[122:123], v[108:109], v[118:119] op_sel_hi:[1,0]
	v_pk_mul_f32 v[120:121], v[110:111], v[118:119] op_sel_hi:[1,0]
	v_exp_f32_e32 v117, v122
	v_mul_f32_e32 v116, v116, v116
	v_add_f32_e32 v117, 1.0, v117
	v_rcp_f32_e32 v122, v117
	v_exp_f32_e32 v117, v123
	s_nop 0
	v_add_f32_e32 v117, 1.0, v117
	v_rcp_f32_e32 v123, v117
	v_exp_f32_e32 v117, v120
	s_nop 0
	v_add_f32_e32 v117, 1.0, v117
	v_rcp_f32_e32 v120, v117
	v_exp_f32_e32 v117, v121
	s_nop 0
	v_add_f32_e32 v117, 1.0, v117
	v_rcp_f32_e32 v121, v117
	v_pk_mul_f32 v[108:109], v[116:117], v[122:123] op_sel_hi:[0,1]
	v_pk_mul_f32 v[104:105], v[104:105], v[108:109]
	v_pk_mul_f32 v[110:111], v[116:117], v[120:121] op_sel_hi:[0,1]
	v_pk_mul_f32 v[106:107], v[106:107], v[110:111]
	v_cvt_pk_bf16_f32 v108, v105, s0
	v_cvt_pk_bf16_f32 v104, v104, s0
	v_cvt_pk_bf16_f32 v105, v106, v107
	v_lshlrev_b32_e32 v106, 16, v108
	v_pk_mul_f32 v[108:109], v[100:101], v[118:119] op_sel_hi:[1,0]
	v_or_b32_sdwa v104, v106, v104 dst_sel:DWORD dst_unused:UNUSED_PAD src0_sel:DWORD src1_sel:WORD_0
	v_pk_mul_f32 v[106:107], v[102:103], v[118:119] op_sel_hi:[1,0]
	v_exp_f32_e32 v108, v108
	v_exp_f32_e32 v109, v109
	v_exp_f32_e32 v106, v106
	v_exp_f32_e32 v107, v107
	v_add_f32_e32 v108, 1.0, v108
	v_add_f32_e32 v109, 1.0, v109
	v_rcp_f32_e32 v108, v108
	v_rcp_f32_e32 v109, v109
	v_add_f32_e32 v106, 1.0, v106
	v_add_f32_e32 v107, 1.0, v107
	v_rcp_f32_e32 v106, v106
	v_rcp_f32_e32 v107, v107
	v_pk_mul_f32 v[100:101], v[116:117], v[108:109] op_sel_hi:[0,1]
	v_pk_mul_f32 v[96:97], v[96:97], v[100:101]
	v_pk_mul_f32 v[102:103], v[116:117], v[106:107] op_sel_hi:[0,1]
	v_pk_mul_f32 v[98:99], v[98:99], v[102:103]
	v_cvt_pk_bf16_f32 v106, v96, v97
	v_mad_i64_i32 v[96:97], s[18:19], v146, s9, v[112:113]
	v_cvt_pk_bf16_f32 v107, v98, v99
	v_lshl_add_u64 v[96:97], v[96:97], 0, v[114:115]
	global_store_dwordx4 v[96:97], v[104:107], off
	v_fmamk_f32 v96, v233, 0x3a800000, v194
	v_cmp_gt_f32_e32 vcc, s2, v96
	v_mul_f32_e32 v97, 0x4b800000, v96
	s_nop 0
	v_cndmask_b32_e32 v96, v96, v97, vcc
	v_rsq_f32_e32 v96, v96
	s_nop 0
	v_mul_f32_e32 v97, 0x45800000, v96
	v_cndmask_b32_e32 v97, v96, v97, vcc
	v_mul_f32_e32 v96, 0xbfb8aa3b, v97
	v_pk_mul_f32 v[102:103], v[92:93], v[96:97] op_sel_hi:[1,0]
	v_mul_f32_e32 v98, v97, v97
	v_pk_mul_f32 v[100:101], v[94:95], v[96:97] op_sel_hi:[1,0]
	v_exp_f32_e32 v97, v102
	s_nop 0
	v_add_f32_e32 v97, 1.0, v97
	v_rcp_f32_e32 v102, v97
	v_exp_f32_e32 v97, v103
	s_nop 0
	v_add_f32_e32 v97, 1.0, v97
	v_rcp_f32_e32 v103, v97
	v_exp_f32_e32 v97, v100
	v_pk_mul_f32 v[92:93], v[98:99], v[102:103] op_sel_hi:[0,1]
	v_add_f32_e32 v97, 1.0, v97
	v_rcp_f32_e32 v100, v97
	v_exp_f32_e32 v97, v101
	v_pk_mul_f32 v[88:89], v[88:89], v[92:93]
	v_add_f32_e32 v97, 1.0, v97
	v_rcp_f32_e32 v101, v97
	v_cvt_pk_bf16_f32 v92, v89, s0
	v_cvt_pk_bf16_f32 v88, v88, s0
	v_pk_mul_f32 v[94:95], v[98:99], v[100:101] op_sel_hi:[0,1]
	v_pk_mul_f32 v[90:91], v[90:91], v[94:95]
	s_nop 0
	v_cvt_pk_bf16_f32 v89, v90, v91
	v_lshlrev_b32_e32 v90, 16, v92
	v_pk_mul_f32 v[92:93], v[84:85], v[96:97] op_sel_hi:[1,0]
	v_or_b32_sdwa v88, v90, v88 dst_sel:DWORD dst_unused:UNUSED_PAD src0_sel:DWORD src1_sel:WORD_0
	v_pk_mul_f32 v[90:91], v[86:87], v[96:97] op_sel_hi:[1,0]
	v_exp_f32_e32 v92, v92
	v_exp_f32_e32 v93, v93
	v_exp_f32_e32 v90, v90
	v_exp_f32_e32 v91, v91
	v_add_f32_e32 v92, 1.0, v92
	v_add_f32_e32 v93, 1.0, v93
	v_rcp_f32_e32 v92, v92
	v_rcp_f32_e32 v93, v93
	v_add_f32_e32 v90, 1.0, v90
	v_add_f32_e32 v91, 1.0, v91
	v_rcp_f32_e32 v90, v90
	v_rcp_f32_e32 v91, v91
	v_pk_mul_f32 v[84:85], v[98:99], v[92:93] op_sel_hi:[0,1]
	v_pk_mul_f32 v[80:81], v[80:81], v[84:85]
	v_pk_mul_f32 v[86:87], v[98:99], v[90:91] op_sel_hi:[0,1]
	v_pk_mul_f32 v[82:83], v[82:83], v[86:87]
	v_cvt_pk_bf16_f32 v90, v80, v81
	v_mad_i64_i32 v[80:81], s[18:19], v144, s9, v[112:113]
	v_cvt_pk_bf16_f32 v91, v82, v83
	v_lshl_add_u64 v[80:81], v[80:81], 0, v[114:115]
	global_store_dwordx4 v[80:81], v[88:91], off
	v_fmamk_f32 v80, v234, 0x3a800000, v194
	v_cmp_gt_f32_e32 vcc, s2, v80
	v_mul_f32_e32 v81, 0x4b800000, v80
	s_nop 0
	v_cndmask_b32_e32 v80, v80, v81, vcc
	v_rsq_f32_e32 v80, v80
	s_nop 0
	v_mul_f32_e32 v81, 0x45800000, v80
	v_cndmask_b32_e32 v81, v80, v81, vcc
	v_mul_f32_e32 v80, 0xbfb8aa3b, v81
	v_pk_mul_f32 v[86:87], v[76:77], v[80:81] op_sel_hi:[1,0]
	v_mul_f32_e32 v82, v81, v81
	v_pk_mul_f32 v[84:85], v[78:79], v[80:81] op_sel_hi:[1,0]
	v_exp_f32_e32 v81, v86
	s_nop 0
	v_add_f32_e32 v81, 1.0, v81
	v_rcp_f32_e32 v86, v81
	v_exp_f32_e32 v81, v87
	s_nop 0
	v_add_f32_e32 v81, 1.0, v81
	v_rcp_f32_e32 v87, v81
	v_exp_f32_e32 v81, v84
	v_pk_mul_f32 v[76:77], v[82:83], v[86:87] op_sel_hi:[0,1]
	v_add_f32_e32 v81, 1.0, v81
	v_rcp_f32_e32 v84, v81
	v_exp_f32_e32 v81, v85
	v_pk_mul_f32 v[72:73], v[72:73], v[76:77]
	v_add_f32_e32 v81, 1.0, v81
	v_rcp_f32_e32 v85, v81
	v_cvt_pk_bf16_f32 v76, v73, s0
	v_cvt_pk_bf16_f32 v72, v72, s0
	v_pk_mul_f32 v[78:79], v[82:83], v[84:85] op_sel_hi:[0,1]
	v_pk_mul_f32 v[74:75], v[74:75], v[78:79]
	s_nop 0
	v_cvt_pk_bf16_f32 v73, v74, v75
	v_lshlrev_b32_e32 v74, 16, v76
	v_pk_mul_f32 v[76:77], v[68:69], v[80:81] op_sel_hi:[1,0]
	v_or_b32_sdwa v72, v74, v72 dst_sel:DWORD dst_unused:UNUSED_PAD src0_sel:DWORD src1_sel:WORD_0
	v_pk_mul_f32 v[74:75], v[70:71], v[80:81] op_sel_hi:[1,0]
	v_exp_f32_e32 v76, v76
	v_exp_f32_e32 v77, v77
	v_exp_f32_e32 v74, v74
	v_exp_f32_e32 v75, v75
	v_add_f32_e32 v76, 1.0, v76
	v_add_f32_e32 v77, 1.0, v77
	v_rcp_f32_e32 v76, v76
	v_rcp_f32_e32 v77, v77
	v_add_f32_e32 v74, 1.0, v74
	v_add_f32_e32 v75, 1.0, v75
	v_rcp_f32_e32 v74, v74
	v_rcp_f32_e32 v75, v75
	v_pk_mul_f32 v[68:69], v[82:83], v[76:77] op_sel_hi:[0,1]
	v_pk_mul_f32 v[64:65], v[64:65], v[68:69]
	v_add_u32_e32 v69, 0x90, v138
	v_pk_mul_f32 v[70:71], v[82:83], v[74:75] op_sel_hi:[0,1]
	v_pk_mul_f32 v[66:67], v[66:67], v[70:71]
	v_cvt_pk_bf16_f32 v74, v64, v65
	v_mad_i64_i32 v[64:65], s[18:19], v142, s9, v[112:113]
	v_cvt_pk_bf16_f32 v75, v66, v67
	v_lshl_add_u64 v[64:65], v[64:65], 0, v[114:115]
	global_store_dwordx4 v[64:65], v[72:75], off
	v_add_u32_e32 v67, 0x80, v138
	v_add_u32_e32 v66, 0xa0, v138
	v_add_u32_e32 v64, 0xb0, v138
	v_fmamk_f32 v68, v235, 0x3a800000, v194
	v_cmp_gt_f32_e32 vcc, s2, v68
	v_mul_f32_e32 v70, 0x4b800000, v68
	s_nop 0
	v_cndmask_b32_e32 v68, v68, v70, vcc
	v_rsq_f32_e32 v68, v68
	s_nop 0
	v_mul_f32_e32 v70, 0x45800000, v68
	v_cndmask_b32_e32 v70, v68, v70, vcc
	v_mul_f32_e32 v68, 0xbfb8aa3b, v70
	v_pk_mul_f32 v[74:75], v[60:61], v[68:69] op_sel_hi:[1,0]
	v_pk_mul_f32 v[72:73], v[62:63], v[68:69] op_sel_hi:[1,0]
	v_exp_f32_e32 v74, v74
	v_exp_f32_e32 v75, v75
	v_exp_f32_e32 v72, v72
	v_exp_f32_e32 v73, v73
	v_add_f32_e32 v74, 1.0, v74
	v_add_f32_e32 v75, 1.0, v75
	v_rcp_f32_e32 v74, v74
	v_rcp_f32_e32 v75, v75
	v_add_f32_e32 v72, 1.0, v72
	v_add_f32_e32 v73, 1.0, v73
	v_rcp_f32_e32 v72, v72
	v_rcp_f32_e32 v73, v73
	v_mul_f32_e32 v70, v70, v70
	v_pk_mul_f32 v[60:61], v[70:71], v[74:75] op_sel_hi:[0,1]
	v_pk_mul_f32 v[56:57], v[56:57], v[60:61]
	v_pk_mul_f32 v[62:63], v[70:71], v[72:73] op_sel_hi:[0,1]
	v_pk_mul_f32 v[58:59], v[58:59], v[62:63]
	v_cvt_pk_bf16_f32 v60, v57, s0
	v_cvt_pk_bf16_f32 v56, v56, s0
	v_cvt_pk_bf16_f32 v57, v58, v59
	v_lshlrev_b32_e32 v58, 16, v60
	v_pk_mul_f32 v[60:61], v[52:53], v[68:69] op_sel_hi:[1,0]
	v_or_b32_sdwa v56, v58, v56 dst_sel:DWORD dst_unused:UNUSED_PAD src0_sel:DWORD src1_sel:WORD_0
	v_pk_mul_f32 v[58:59], v[54:55], v[68:69] op_sel_hi:[1,0]
	v_exp_f32_e32 v60, v60
	v_exp_f32_e32 v61, v61
	v_exp_f32_e32 v58, v58
	v_exp_f32_e32 v59, v59
	v_add_f32_e32 v60, 1.0, v60
	v_add_f32_e32 v61, 1.0, v61
	v_rcp_f32_e32 v60, v60
	v_rcp_f32_e32 v61, v61
	v_add_f32_e32 v58, 1.0, v58
	v_add_f32_e32 v59, 1.0, v59
	v_rcp_f32_e32 v58, v58
	v_rcp_f32_e32 v59, v59
	v_pk_mul_f32 v[52:53], v[70:71], v[60:61] op_sel_hi:[0,1]
	v_pk_mul_f32 v[48:49], v[48:49], v[52:53]
	v_pk_mul_f32 v[54:55], v[70:71], v[58:59] op_sel_hi:[0,1]
	v_pk_mul_f32 v[50:51], v[50:51], v[54:55]
	v_cvt_pk_bf16_f32 v58, v48, v49
	v_mad_i64_i32 v[48:49], s[18:19], v67, s9, v[112:113]
	v_cvt_pk_bf16_f32 v59, v50, v51
	v_lshl_add_u64 v[48:49], v[48:49], 0, v[114:115]
	global_store_dwordx4 v[48:49], v[56:59], off
	v_fmamk_f32 v48, v236, 0x3a800000, v194
	v_cmp_gt_f32_e32 vcc, s2, v48
	v_mul_f32_e32 v49, 0x4b800000, v48
	s_nop 0
	v_cndmask_b32_e32 v48, v48, v49, vcc
	v_rsq_f32_e32 v48, v48
	s_nop 0
	v_mul_f32_e32 v49, 0x45800000, v48
	v_cndmask_b32_e32 v49, v48, v49, vcc
	v_mul_f32_e32 v48, 0xbfb8aa3b, v49
	v_pk_mul_f32 v[54:55], v[44:45], v[48:49] op_sel_hi:[1,0]
	v_mul_f32_e32 v50, v49, v49
	v_pk_mul_f32 v[52:53], v[46:47], v[48:49] op_sel_hi:[1,0]
	v_exp_f32_e32 v49, v54
	s_nop 0
	v_add_f32_e32 v49, 1.0, v49
	v_rcp_f32_e32 v54, v49
	v_exp_f32_e32 v49, v55
	s_nop 0
	v_add_f32_e32 v49, 1.0, v49
	v_rcp_f32_e32 v55, v49
	v_exp_f32_e32 v49, v52
	v_pk_mul_f32 v[44:45], v[50:51], v[54:55] op_sel_hi:[0,1]
	v_add_f32_e32 v49, 1.0, v49
	v_rcp_f32_e32 v52, v49
	v_exp_f32_e32 v49, v53
	v_pk_mul_f32 v[40:41], v[40:41], v[44:45]
	v_add_f32_e32 v49, 1.0, v49
	v_rcp_f32_e32 v53, v49
	v_cvt_pk_bf16_f32 v44, v41, s0
	v_cvt_pk_bf16_f32 v40, v40, s0
	v_pk_mul_f32 v[46:47], v[50:51], v[52:53] op_sel_hi:[0,1]
	v_pk_mul_f32 v[42:43], v[42:43], v[46:47]
	s_nop 0
	v_cvt_pk_bf16_f32 v41, v42, v43
	v_lshlrev_b32_e32 v42, 16, v44
	v_pk_mul_f32 v[44:45], v[36:37], v[48:49] op_sel_hi:[1,0]
	v_or_b32_sdwa v40, v42, v40 dst_sel:DWORD dst_unused:UNUSED_PAD src0_sel:DWORD src1_sel:WORD_0
	v_pk_mul_f32 v[42:43], v[38:39], v[48:49] op_sel_hi:[1,0]
	v_exp_f32_e32 v44, v44
	v_exp_f32_e32 v45, v45
	v_exp_f32_e32 v42, v42
	v_exp_f32_e32 v43, v43
	v_add_f32_e32 v44, 1.0, v44
	v_add_f32_e32 v45, 1.0, v45
	v_rcp_f32_e32 v44, v44
	v_rcp_f32_e32 v45, v45
	v_add_f32_e32 v42, 1.0, v42
	v_add_f32_e32 v43, 1.0, v43
	v_rcp_f32_e32 v42, v42
	v_rcp_f32_e32 v43, v43
	v_pk_mul_f32 v[36:37], v[50:51], v[44:45] op_sel_hi:[0,1]
	v_pk_mul_f32 v[32:33], v[32:33], v[36:37]
	v_pk_mul_f32 v[38:39], v[50:51], v[42:43] op_sel_hi:[0,1]
	v_pk_mul_f32 v[34:35], v[34:35], v[38:39]
	v_cvt_pk_bf16_f32 v42, v32, v33
	v_mad_i64_i32 v[32:33], s[18:19], v69, s9, v[112:113]
	v_cvt_pk_bf16_f32 v43, v34, v35
	v_lshl_add_u64 v[32:33], v[32:33], 0, v[114:115]
	global_store_dwordx4 v[32:33], v[40:43], off
	v_fmamk_f32 v32, v237, 0x3a800000, v194
	v_cmp_gt_f32_e32 vcc, s2, v32
	v_mul_f32_e32 v33, 0x4b800000, v32
	s_nop 0
	v_cndmask_b32_e32 v32, v32, v33, vcc
	v_rsq_f32_e32 v32, v32
	s_nop 0
	v_mul_f32_e32 v33, 0x45800000, v32
	v_cndmask_b32_e32 v33, v32, v33, vcc
	v_mul_f32_e32 v32, 0xbfb8aa3b, v33
	v_pk_mul_f32 v[38:39], v[28:29], v[32:33] op_sel_hi:[1,0]
	v_mul_f32_e32 v34, v33, v33
	v_pk_mul_f32 v[36:37], v[30:31], v[32:33] op_sel_hi:[1,0]
	v_exp_f32_e32 v33, v38
	s_nop 0
	v_add_f32_e32 v33, 1.0, v33
	v_rcp_f32_e32 v38, v33
	v_exp_f32_e32 v33, v39
	s_nop 0
	v_add_f32_e32 v33, 1.0, v33
	v_rcp_f32_e32 v39, v33
	v_exp_f32_e32 v33, v36
	v_pk_mul_f32 v[28:29], v[34:35], v[38:39] op_sel_hi:[0,1]
	v_add_f32_e32 v33, 1.0, v33
	v_rcp_f32_e32 v36, v33
	v_exp_f32_e32 v33, v37
	v_pk_mul_f32 v[24:25], v[24:25], v[28:29]
	v_add_f32_e32 v33, 1.0, v33
	v_rcp_f32_e32 v37, v33
	v_cvt_pk_bf16_f32 v28, v25, s0
	v_cvt_pk_bf16_f32 v24, v24, s0
	v_pk_mul_f32 v[30:31], v[34:35], v[36:37] op_sel_hi:[0,1]
	v_pk_mul_f32 v[26:27], v[26:27], v[30:31]
	s_nop 0
	v_cvt_pk_bf16_f32 v25, v26, v27
	v_lshlrev_b32_e32 v26, 16, v28
	v_pk_mul_f32 v[28:29], v[20:21], v[32:33] op_sel_hi:[1,0]
	v_or_b32_sdwa v24, v26, v24 dst_sel:DWORD dst_unused:UNUSED_PAD src0_sel:DWORD src1_sel:WORD_0
	v_pk_mul_f32 v[26:27], v[22:23], v[32:33] op_sel_hi:[1,0]
	v_exp_f32_e32 v28, v28
	v_exp_f32_e32 v29, v29
	v_exp_f32_e32 v26, v26
	v_exp_f32_e32 v27, v27
	v_add_f32_e32 v28, 1.0, v28
	v_add_f32_e32 v29, 1.0, v29
	v_rcp_f32_e32 v28, v28
	v_rcp_f32_e32 v29, v29
	v_add_f32_e32 v26, 1.0, v26
	v_add_f32_e32 v27, 1.0, v27
	v_rcp_f32_e32 v26, v26
	v_rcp_f32_e32 v27, v27
	v_pk_mul_f32 v[20:21], v[34:35], v[28:29] op_sel_hi:[0,1]
	v_pk_mul_f32 v[16:17], v[16:17], v[20:21]
	v_pk_mul_f32 v[22:23], v[34:35], v[26:27] op_sel_hi:[0,1]
	v_pk_mul_f32 v[18:19], v[18:19], v[22:23]
	v_cvt_pk_bf16_f32 v26, v16, v17
	v_mad_i64_i32 v[16:17], s[18:19], v66, s9, v[112:113]
	v_cvt_pk_bf16_f32 v27, v18, v19
	v_lshl_add_u64 v[16:17], v[16:17], 0, v[114:115]
	global_store_dwordx4 v[16:17], v[24:27], off
	v_fmamk_f32 v16, v238, 0x3a800000, v194
	v_cmp_gt_f32_e32 vcc, s2, v16
	v_mul_f32_e32 v17, 0x4b800000, v16
	s_nop 0
	v_cndmask_b32_e32 v16, v16, v17, vcc
	v_rsq_f32_e32 v16, v16
	s_nop 0
	v_mul_f32_e32 v17, 0x45800000, v16
	v_cndmask_b32_e32 v17, v16, v17, vcc
	v_mul_f32_e32 v16, 0xbfb8aa3b, v17
	v_pk_mul_f32 v[22:23], v[12:13], v[16:17] op_sel_hi:[1,0]
	v_mul_f32_e32 v18, v17, v17
	v_pk_mul_f32 v[20:21], v[14:15], v[16:17] op_sel_hi:[1,0]
	v_exp_f32_e32 v17, v22
	s_and_b64 vcc, exec, s[0:1]
	v_add_f32_e32 v17, 1.0, v17
	v_rcp_f32_e32 v22, v17
	v_exp_f32_e32 v17, v23
	s_nop 0
	v_add_f32_e32 v17, 1.0, v17
	v_rcp_f32_e32 v23, v17
	v_exp_f32_e32 v17, v20
	v_pk_mul_f32 v[12:13], v[18:19], v[22:23] op_sel_hi:[0,1]
	v_add_f32_e32 v17, 1.0, v17
	v_rcp_f32_e32 v20, v17
	v_exp_f32_e32 v17, v21
	v_pk_mul_f32 v[8:9], v[8:9], v[12:13]
	v_add_f32_e32 v17, 1.0, v17
	v_rcp_f32_e32 v21, v17
	v_cvt_pk_bf16_f32 v12, v9, s0
	v_cvt_pk_bf16_f32 v8, v8, s0
	v_pk_mul_f32 v[14:15], v[18:19], v[20:21] op_sel_hi:[0,1]
	v_pk_mul_f32 v[10:11], v[10:11], v[14:15]
	s_nop 0
	v_cvt_pk_bf16_f32 v9, v10, v11
	v_lshlrev_b32_e32 v10, 16, v12
	v_pk_mul_f32 v[12:13], v[4:5], v[16:17] op_sel_hi:[1,0]
	v_or_b32_sdwa v8, v10, v8 dst_sel:DWORD dst_unused:UNUSED_PAD src0_sel:DWORD src1_sel:WORD_0
	v_pk_mul_f32 v[10:11], v[6:7], v[16:17] op_sel_hi:[1,0]
	v_exp_f32_e32 v12, v12
	v_exp_f32_e32 v13, v13
	v_exp_f32_e32 v10, v10
	v_exp_f32_e32 v11, v11
	v_add_f32_e32 v12, 1.0, v12
	v_add_f32_e32 v13, 1.0, v13
	v_rcp_f32_e32 v12, v12
	v_rcp_f32_e32 v13, v13
	v_add_f32_e32 v10, 1.0, v10
	v_add_f32_e32 v11, 1.0, v11
	v_rcp_f32_e32 v10, v10
	v_rcp_f32_e32 v11, v11
	v_pk_mul_f32 v[4:5], v[18:19], v[12:13] op_sel_hi:[0,1]
	v_pk_mul_f32 v[0:1], v[0:1], v[4:5]
	v_pk_mul_f32 v[6:7], v[18:19], v[10:11] op_sel_hi:[0,1]
	v_pk_mul_f32 v[2:3], v[2:3], v[6:7]
	v_cvt_pk_bf16_f32 v10, v0, v1
	v_mad_i64_i32 v[0:1], s[18:19], v64, s9, v[112:113]
	v_cvt_pk_bf16_f32 v11, v2, v3
	v_lshl_add_u64 v[0:1], v[0:1], 0, v[114:115]
	s_mov_b64 s[18:19], s[14:15]
	global_store_dwordx4 v[0:1], v[8:11], off
	s_cbranch_vccz .LBB0_2801
	s_waitcnt vmcnt(0)
	s_cmpk_gt_u32 s25, 0xff
	s_cbranch_scc1 .LBB0_2808
	s_barrier

.LBB0_3617:
	s_add_u32 s33, s20, 0x100
	v_mov_b32_e32 v0, 0
	s_addc_u32 s43, s21, 0
	s_mov_b32 s44, -2
	v_mov_b32_e32 v1, v0
	v_mov_b32_e32 v2, v0
	v_mov_b32_e32 v3, v0
	v_mov_b32_e32 v4, v0
	v_mov_b32_e32 v5, v0
	v_mov_b32_e32 v6, v0
	v_mov_b32_e32 v7, v0
	v_mov_b32_e32 v16, v0
	v_mov_b32_e32 v17, v0
	v_mov_b32_e32 v18, v0
	v_mov_b32_e32 v19, v0
	v_mov_b32_e32 v20, v0
	v_mov_b32_e32 v21, v0
	v_mov_b32_e32 v22, v0
	v_mov_b32_e32 v23, v0
	v_mov_b32_e32 v32, v0
	v_mov_b32_e32 v33, v0
	v_mov_b32_e32 v34, v0
	v_mov_b32_e32 v35, v0
	v_mov_b32_e32 v36, v0
	v_mov_b32_e32 v37, v0
	v_mov_b32_e32 v38, v0
	v_mov_b32_e32 v39, v0
	v_mov_b32_e32 v48, v0
	v_mov_b32_e32 v49, v0
	v_mov_b32_e32 v50, v0
	v_mov_b32_e32 v51, v0
	v_mov_b32_e32 v52, v0
	v_mov_b32_e32 v53, v0
	v_mov_b32_e32 v54, v0
	v_mov_b32_e32 v55, v0
	v_mov_b32_e32 v8, v0
	v_mov_b32_e32 v9, v0
	v_mov_b32_e32 v10, v0
	v_mov_b32_e32 v11, v0
	v_mov_b32_e32 v12, v0
	v_mov_b32_e32 v13, v0
	v_mov_b32_e32 v14, v0
	v_mov_b32_e32 v15, v0
	v_mov_b32_e32 v24, v0
	v_mov_b32_e32 v25, v0
	v_mov_b32_e32 v26, v0
	v_mov_b32_e32 v27, v0
	v_mov_b32_e32 v28, v0
	v_mov_b32_e32 v29, v0
	v_mov_b32_e32 v30, v0
	v_mov_b32_e32 v31, v0
	v_mov_b32_e32 v40, v0
	v_mov_b32_e32 v41, v0
	v_mov_b32_e32 v42, v0
	v_mov_b32_e32 v43, v0
	v_mov_b32_e32 v44, v0
	v_mov_b32_e32 v45, v0
	v_mov_b32_e32 v46, v0
	v_mov_b32_e32 v47, v0
	v_mov_b32_e32 v56, v0
	v_mov_b32_e32 v57, v0
	v_mov_b32_e32 v58, v0
	v_mov_b32_e32 v59, v0
	v_mov_b32_e32 v60, v0
	v_mov_b32_e32 v61, v0
	v_mov_b32_e32 v62, v0
	v_mov_b32_e32 v63, v0
	s_waitcnt vmcnt(0)
	v_mov_b32_e32 v64, v0
	v_mov_b32_e32 v65, v0
	v_mov_b32_e32 v66, v0
	v_mov_b32_e32 v67, v0
	v_mov_b32_e32 v68, v0
	v_mov_b32_e32 v69, v0
	v_mov_b32_e32 v70, v0
	v_mov_b32_e32 v71, v0
	v_mov_b32_e32 v80, v0
	v_mov_b32_e32 v81, v0
	v_mov_b32_e32 v82, v0
	v_mov_b32_e32 v83, v0
	v_mov_b32_e32 v84, v0
	v_mov_b32_e32 v85, v0
	v_mov_b32_e32 v86, v0
	v_mov_b32_e32 v87, v0
	v_mov_b32_e32 v96, v0
	v_mov_b32_e32 v97, v0
	v_mov_b32_e32 v98, v0
	v_mov_b32_e32 v99, v0
	v_mov_b32_e32 v100, v0
	v_mov_b32_e32 v101, v0
	v_mov_b32_e32 v102, v0
	v_mov_b32_e32 v103, v0
	v_mov_b32_e32 v112, v0
	v_mov_b32_e32 v113, v0
	v_mov_b32_e32 v114, v0
	v_mov_b32_e32 v115, v0
	v_mov_b32_e32 v116, v0
	v_mov_b32_e32 v117, v0
	v_mov_b32_e32 v118, v0
	v_mov_b32_e32 v119, v0
	v_mov_b32_e32 v72, v0
	v_mov_b32_e32 v73, v0
	v_mov_b32_e32 v74, v0
	v_mov_b32_e32 v75, v0
	v_mov_b32_e32 v76, v0
	v_mov_b32_e32 v77, v0
	v_mov_b32_e32 v78, v0
	v_mov_b32_e32 v79, v0
	v_mov_b32_e32 v88, v0
	v_mov_b32_e32 v89, v0
	v_mov_b32_e32 v90, v0
	v_mov_b32_e32 v91, v0
	v_mov_b32_e32 v92, v0
	v_mov_b32_e32 v93, v0
	v_mov_b32_e32 v94, v0
	v_mov_b32_e32 v95, v0
	v_mov_b32_e32 v104, v0
	v_mov_b32_e32 v105, v0
	v_mov_b32_e32 v106, v0
	v_mov_b32_e32 v107, v0
	v_mov_b32_e32 v108, v0
	v_mov_b32_e32 v109, v0
	v_mov_b32_e32 v110, v0
	v_mov_b32_e32 v111, v0
	v_mov_b32_e32 v120, v0
	v_mov_b32_e32 v121, v0
	v_mov_b32_e32 v122, v0
	v_mov_b32_e32 v123, v0
	v_mov_b32_e32 v124, v0
	v_mov_b32_e32 v125, v0
	v_mov_b32_e32 v126, v0
	v_mov_b32_e32 v127, v0
	v_add_u32_e32 v202, 0x10000, v196
	v_add_u32_e32 v203, 0x14000, v196
	v_add_u32_e32 v204, 0x18000, v196
	v_add_u32_e32 v205, 0x1c000, v196
.LBB0_3618:
	s_add_u32 s20, s18, 0x100
	s_addc_u32 s21, s19, 0
	s_add_i32 s45, 0, 0x10000
	ds_read_b128 v[128:131], v202
	ds_read_b128 v[132:135], v202 offset:1024
	ds_read_b128 v[136:139], v202 offset:2048
	ds_read_b128 v[140:143], v202 offset:3072
	s_cmp_eq_u32 s44, 40
	s_cselect_b32 s25, s5, s21
	s_cselect_b32 s24, s4, s20
	s_cselect_b32 s23, s7, s43
	s_cselect_b32 s22, s6, s33
	s_add_i32 m0, s30, 0xc000
	ds_read_b128 v[144:147], v198
	ds_read_b128 v[148:151], v198 offset:1024
	ds_read_b128 v[152:155], v198 offset:2048
	ds_read_b128 v[156:159], v198 offset:3072
	ds_read_b128 v[160:163], v198 offset:4096
	ds_read_b128 v[164:167], v198 offset:5120
	ds_read_b128 v[168:171], v198 offset:6144
	ds_read_b128 v[172:175], v198 offset:7168
	global_load_lds_dwordx4 v214, s[18:19]
	s_add_i32 m0, s30, 0xe000
	s_nop 0
	global_load_lds_dwordx4 v212, s[18:19]
	s_waitcnt lgkmcnt(8)
	s_barrier
	s_waitcnt lgkmcnt(0)
	s_setprio 1
	s_waitcnt lgkmcnt(0)
	v_mfma_f32_16x16x32_bf16 v[124:127], v[128:131], v[144:147], v[124:127]
	v_mfma_f32_16x16x32_bf16 v[120:123], v[136:139], v[144:147], v[120:123]
	v_mfma_f32_16x16x32_bf16 v[108:111], v[128:131], v[152:155], v[108:111]
	v_mfma_f32_16x16x32_bf16 v[104:107], v[136:139], v[152:155], v[104:107]
	v_mfma_f32_16x16x32_bf16 v[92:95], v[128:131], v[160:163], v[92:95]
	v_mfma_f32_16x16x32_bf16 v[88:91], v[136:139], v[160:163], v[88:91]
	v_mfma_f32_16x16x32_bf16 v[76:79], v[128:131], v[168:171], v[76:79]
	v_mfma_f32_16x16x32_bf16 v[72:75], v[136:139], v[168:171], v[72:75]
	v_mfma_f32_16x16x32_bf16 v[124:127], v[132:135], v[148:151], v[124:127]
	v_mfma_f32_16x16x32_bf16 v[120:123], v[140:143], v[148:151], v[120:123]
	v_mfma_f32_16x16x32_bf16 v[108:111], v[132:135], v[156:159], v[108:111]
	v_mfma_f32_16x16x32_bf16 v[104:107], v[140:143], v[156:159], v[104:107]
	v_mfma_f32_16x16x32_bf16 v[92:95], v[132:135], v[164:167], v[92:95]
	v_mfma_f32_16x16x32_bf16 v[88:91], v[140:143], v[164:167], v[88:91]
	v_mfma_f32_16x16x32_bf16 v[76:79], v[132:135], v[172:175], v[76:79]
	v_mfma_f32_16x16x32_bf16 v[72:75], v[140:143], v[172:175], v[72:75]
	s_setprio 0
	s_barrier
	s_add_i32 s46, 0, 0x14000
	s_add_i32 s18, s45, s29
	s_mov_b32 m0, s18
	ds_read_b128 v[176:179], v203
	ds_read_b128 v[180:183], v203 offset:1024
	ds_read_b128 v[184:187], v203 offset:2048
	ds_read_b128 v[188:191], v203 offset:3072
	global_load_lds_dwordx4 v192, s[22:23]
	s_add_i32 m0, s18, 0x2000
	s_nop 0
	global_load_lds_dwordx4 v210, s[22:23]
	s_barrier
	s_waitcnt lgkmcnt(0)
	s_setprio 1
	s_waitcnt lgkmcnt(0)
	v_mfma_f32_16x16x32_bf16 v[116:119], v[176:179], v[144:147], v[116:119]
	v_mfma_f32_16x16x32_bf16 v[112:115], v[184:187], v[144:147], v[112:115]
	v_mfma_f32_16x16x32_bf16 v[100:103], v[176:179], v[152:155], v[100:103]
	v_mfma_f32_16x16x32_bf16 v[96:99], v[184:187], v[152:155], v[96:99]
	v_mfma_f32_16x16x32_bf16 v[84:87], v[176:179], v[160:163], v[84:87]
	v_mfma_f32_16x16x32_bf16 v[80:83], v[184:187], v[160:163], v[80:83]
	v_mfma_f32_16x16x32_bf16 v[68:71], v[176:179], v[168:171], v[68:71]
	v_mfma_f32_16x16x32_bf16 v[64:67], v[184:187], v[168:171], v[64:67]
	v_mfma_f32_16x16x32_bf16 v[116:119], v[180:183], v[148:151], v[116:119]
	v_mfma_f32_16x16x32_bf16 v[112:115], v[188:191], v[148:151], v[112:115]
	v_mfma_f32_16x16x32_bf16 v[100:103], v[180:183], v[156:159], v[100:103]
	v_mfma_f32_16x16x32_bf16 v[96:99], v[188:191], v[156:159], v[96:99]
	v_mfma_f32_16x16x32_bf16 v[84:87], v[180:183], v[164:167], v[84:87]
	v_mfma_f32_16x16x32_bf16 v[80:83], v[188:191], v[164:167], v[80:83]
	v_mfma_f32_16x16x32_bf16 v[68:71], v[180:183], v[172:175], v[68:71]
	v_mfma_f32_16x16x32_bf16 v[64:67], v[188:191], v[172:175], v[64:67]
	s_setprio 0
	s_mov_b32 m0, s30
	s_add_u32 vcc_lo, s24, 0x80
	s_addc_u32 vcc_hi, s25, 0
	s_barrier
	ds_read_b128 v[144:147], v198 offset:16384
	ds_read_b128 v[148:151], v198 offset:17408
	ds_read_b128 v[152:155], v198 offset:18432
	ds_read_b128 v[156:159], v198 offset:19456
	ds_read_b128 v[160:163], v198 offset:20480
	ds_read_b128 v[164:167], v198 offset:21504
	ds_read_b128 v[168:171], v198 offset:22528
	ds_read_b128 v[172:175], v198 offset:23552
	global_load_lds_dwordx4 v206, s[24:25]
	s_mov_b32 m0, s31
	s_nop 0
	global_load_lds_dwordx4 v208, s[24:25]
	s_barrier
	s_waitcnt lgkmcnt(0)
	s_setprio 1
	s_waitcnt lgkmcnt(0)
	v_mfma_f32_16x16x32_bf16 v[60:63], v[128:131], v[144:147], v[60:63]
	v_mfma_f32_16x16x32_bf16 v[56:59], v[136:139], v[144:147], v[56:59]
	v_mfma_f32_16x16x32_bf16 v[44:47], v[128:131], v[152:155], v[44:47]
	v_mfma_f32_16x16x32_bf16 v[40:43], v[136:139], v[152:155], v[40:43]
	v_mfma_f32_16x16x32_bf16 v[28:31], v[128:131], v[160:163], v[28:31]
	v_mfma_f32_16x16x32_bf16 v[24:27], v[136:139], v[160:163], v[24:27]
	v_mfma_f32_16x16x32_bf16 v[12:15], v[128:131], v[168:171], v[12:15]
	v_mfma_f32_16x16x32_bf16 v[8:11], v[136:139], v[168:171], v[8:11]
	v_mfma_f32_16x16x32_bf16 v[60:63], v[132:135], v[148:151], v[60:63]
	v_mfma_f32_16x16x32_bf16 v[56:59], v[140:143], v[148:151], v[56:59]
	v_mfma_f32_16x16x32_bf16 v[44:47], v[132:135], v[156:159], v[44:47]
	v_mfma_f32_16x16x32_bf16 v[40:43], v[140:143], v[156:159], v[40:43]
	v_mfma_f32_16x16x32_bf16 v[28:31], v[132:135], v[164:167], v[28:31]
	v_mfma_f32_16x16x32_bf16 v[24:27], v[140:143], v[164:167], v[24:27]
	v_mfma_f32_16x16x32_bf16 v[12:15], v[132:135], v[172:175], v[12:15]
	v_mfma_f32_16x16x32_bf16 v[8:11], v[140:143], v[172:175], v[8:11]
	s_setprio 0
	s_barrier
	s_add_u32 s18, s22, 0xb0000
	s_addc_u32 s19, s23, 0
	s_add_i32 s45, s46, s29
	s_mov_b32 m0, s45
	s_nop 0
	global_load_lds_dwordx4 v192, s[18:19]
	s_add_i32 m0, s45, 0x2000
	s_nop 0
	global_load_lds_dwordx4 v210, s[18:19]
	s_waitcnt vmcnt(6)
	s_barrier
	s_setprio 1
	v_mfma_f32_16x16x32_bf16 v[52:55], v[176:179], v[144:147], v[52:55]
	v_mfma_f32_16x16x32_bf16 v[48:51], v[184:187], v[144:147], v[48:51]
	v_mfma_f32_16x16x32_bf16 v[36:39], v[176:179], v[152:155], v[36:39]
	v_mfma_f32_16x16x32_bf16 v[32:35], v[184:187], v[152:155], v[32:35]
	v_mfma_f32_16x16x32_bf16 v[20:23], v[176:179], v[160:163], v[20:23]
	v_mfma_f32_16x16x32_bf16 v[16:19], v[184:187], v[160:163], v[16:19]
	v_mfma_f32_16x16x32_bf16 v[4:7], v[176:179], v[168:171], v[4:7]
	v_mfma_f32_16x16x32_bf16 v[0:3], v[184:187], v[168:171], v[0:3]
	v_mfma_f32_16x16x32_bf16 v[52:55], v[180:183], v[148:151], v[52:55]
	v_mfma_f32_16x16x32_bf16 v[48:51], v[188:191], v[148:151], v[48:51]
	v_mfma_f32_16x16x32_bf16 v[36:39], v[180:183], v[156:159], v[36:39]
	v_mfma_f32_16x16x32_bf16 v[32:35], v[188:191], v[156:159], v[32:35]
	v_mfma_f32_16x16x32_bf16 v[20:23], v[180:183], v[164:167], v[20:23]
	v_mfma_f32_16x16x32_bf16 v[16:19], v[188:191], v[164:167], v[16:19]
	v_mfma_f32_16x16x32_bf16 v[4:7], v[180:183], v[172:175], v[4:7]
	v_mfma_f32_16x16x32_bf16 v[0:3], v[188:191], v[172:175], v[0:3]
	s_setprio 0
	s_add_i32 s45, 0, 0x18000
	s_barrier
	ds_read_b128 v[128:131], v204
	ds_read_b128 v[132:135], v204 offset:1024
	ds_read_b128 v[136:139], v204 offset:2048
	ds_read_b128 v[140:143], v204 offset:3072
	s_add_u32 s18, s24, 0xb0000
	s_addc_u32 s19, s25, 0
	s_mov_b32 m0, s34
	ds_read_b128 v[144:147], v198 offset:32768
	ds_read_b128 v[148:151], v198 offset:33792
	ds_read_b128 v[152:155], v198 offset:34816
	ds_read_b128 v[156:159], v198 offset:35840
	ds_read_b128 v[160:163], v198 offset:36864
	ds_read_b128 v[164:167], v198 offset:37888
	ds_read_b128 v[168:171], v198 offset:38912
	ds_read_b128 v[172:175], v198 offset:39936
	global_load_lds_dwordx4 v206, s[18:19]
	s_mov_b32 m0, s35
	s_nop 0
	global_load_lds_dwordx4 v208, s[18:19]
	s_waitcnt lgkmcnt(8)
	s_barrier
	s_waitcnt lgkmcnt(0)
	s_setprio 1
	s_waitcnt lgkmcnt(0)
	v_mfma_f32_16x16x32_bf16 v[124:127], v[128:131], v[144:147], v[124:127]
	v_mfma_f32_16x16x32_bf16 v[120:123], v[136:139], v[144:147], v[120:123]
	v_mfma_f32_16x16x32_bf16 v[108:111], v[128:131], v[152:155], v[108:111]
	v_mfma_f32_16x16x32_bf16 v[104:107], v[136:139], v[152:155], v[104:107]
	v_mfma_f32_16x16x32_bf16 v[92:95], v[128:131], v[160:163], v[92:95]
	v_mfma_f32_16x16x32_bf16 v[88:91], v[136:139], v[160:163], v[88:91]
	v_mfma_f32_16x16x32_bf16 v[76:79], v[128:131], v[168:171], v[76:79]
	v_mfma_f32_16x16x32_bf16 v[72:75], v[136:139], v[168:171], v[72:75]
	v_mfma_f32_16x16x32_bf16 v[124:127], v[132:135], v[148:151], v[124:127]
	v_mfma_f32_16x16x32_bf16 v[120:123], v[140:143], v[148:151], v[120:123]
	v_mfma_f32_16x16x32_bf16 v[108:111], v[132:135], v[156:159], v[108:111]
	v_mfma_f32_16x16x32_bf16 v[104:107], v[140:143], v[156:159], v[104:107]
	v_mfma_f32_16x16x32_bf16 v[92:95], v[132:135], v[164:167], v[92:95]
	v_mfma_f32_16x16x32_bf16 v[88:91], v[140:143], v[164:167], v[88:91]
	v_mfma_f32_16x16x32_bf16 v[76:79], v[132:135], v[172:175], v[76:79]
	v_mfma_f32_16x16x32_bf16 v[72:75], v[140:143], v[172:175], v[72:75]
	s_setprio 0
	s_barrier
	s_add_i32 s24, 0, 0x1c000
	s_add_i32 s18, s45, s29
	s_add_u32 s100, s22, 0x80
	s_addc_u32 s101, s23, 0
	s_mov_b32 m0, s18
	ds_read_b128 v[176:179], v205
	ds_read_b128 v[180:183], v205 offset:1024
	ds_read_b128 v[184:187], v205 offset:2048
	ds_read_b128 v[188:191], v205 offset:3072
	global_load_lds_dwordx4 v192, s[100:101]
	s_add_i32 m0, s18, 0x2000
	s_nop 0
	global_load_lds_dwordx4 v210, s[100:101]
	s_barrier
	s_waitcnt lgkmcnt(0)
	s_setprio 1
	s_waitcnt lgkmcnt(0)
	v_mfma_f32_16x16x32_bf16 v[116:119], v[176:179], v[144:147], v[116:119]
	v_mfma_f32_16x16x32_bf16 v[112:115], v[184:187], v[144:147], v[112:115]
	v_mfma_f32_16x16x32_bf16 v[100:103], v[176:179], v[152:155], v[100:103]
	v_mfma_f32_16x16x32_bf16 v[96:99], v[184:187], v[152:155], v[96:99]
	v_mfma_f32_16x16x32_bf16 v[84:87], v[176:179], v[160:163], v[84:87]
	v_mfma_f32_16x16x32_bf16 v[80:83], v[184:187], v[160:163], v[80:83]
	v_mfma_f32_16x16x32_bf16 v[68:71], v[176:179], v[168:171], v[68:71]
	v_mfma_f32_16x16x32_bf16 v[64:67], v[184:187], v[168:171], v[64:67]
	v_mfma_f32_16x16x32_bf16 v[116:119], v[180:183], v[148:151], v[116:119]
	v_mfma_f32_16x16x32_bf16 v[112:115], v[188:191], v[148:151], v[112:115]
	v_mfma_f32_16x16x32_bf16 v[100:103], v[180:183], v[156:159], v[100:103]
	v_mfma_f32_16x16x32_bf16 v[96:99], v[188:191], v[156:159], v[96:99]
	v_mfma_f32_16x16x32_bf16 v[84:87], v[180:183], v[164:167], v[84:87]
	v_mfma_f32_16x16x32_bf16 v[80:83], v[188:191], v[164:167], v[80:83]
	v_mfma_f32_16x16x32_bf16 v[68:71], v[180:183], v[172:175], v[68:71]
	v_mfma_f32_16x16x32_bf16 v[64:67], v[188:191], v[172:175], v[64:67]
	s_setprio 0
	s_mov_b32 m0, s36
	s_barrier
	ds_read_b128 v[144:147], v198 offset:49152
	ds_read_b128 v[148:151], v198 offset:50176
	ds_read_b128 v[152:155], v198 offset:51200
	ds_read_b128 v[156:159], v198 offset:52224
	ds_read_b128 v[160:163], v198 offset:53248
	ds_read_b128 v[164:167], v198 offset:54272
	ds_read_b128 v[168:171], v198 offset:55296
	ds_read_b128 v[172:175], v198 offset:56320
	global_load_lds_dwordx4 v206, vcc
	s_mov_b32 m0, s37
	s_nop 0
	global_load_lds_dwordx4 v208, vcc
	s_barrier
	s_waitcnt lgkmcnt(0)
	s_setprio 1
	s_waitcnt lgkmcnt(0)
	v_mfma_f32_16x16x32_bf16 v[60:63], v[128:131], v[144:147], v[60:63]
	v_mfma_f32_16x16x32_bf16 v[56:59], v[136:139], v[144:147], v[56:59]
	v_mfma_f32_16x16x32_bf16 v[44:47], v[128:131], v[152:155], v[44:47]
	v_mfma_f32_16x16x32_bf16 v[40:43], v[136:139], v[152:155], v[40:43]
	v_mfma_f32_16x16x32_bf16 v[28:31], v[128:131], v[160:163], v[28:31]
	v_mfma_f32_16x16x32_bf16 v[24:27], v[136:139], v[160:163], v[24:27]
	v_mfma_f32_16x16x32_bf16 v[12:15], v[128:131], v[168:171], v[12:15]
	v_mfma_f32_16x16x32_bf16 v[8:11], v[136:139], v[168:171], v[8:11]
	v_mfma_f32_16x16x32_bf16 v[60:63], v[132:135], v[148:151], v[60:63]
	v_mfma_f32_16x16x32_bf16 v[56:59], v[140:143], v[148:151], v[56:59]
	v_mfma_f32_16x16x32_bf16 v[44:47], v[132:135], v[156:159], v[44:47]
	v_mfma_f32_16x16x32_bf16 v[40:43], v[140:143], v[156:159], v[40:43]
	v_mfma_f32_16x16x32_bf16 v[28:31], v[132:135], v[164:167], v[28:31]
	v_mfma_f32_16x16x32_bf16 v[24:27], v[140:143], v[164:167], v[24:27]
	v_mfma_f32_16x16x32_bf16 v[12:15], v[132:135], v[172:175], v[12:15]
	v_mfma_f32_16x16x32_bf16 v[8:11], v[140:143], v[172:175], v[8:11]
	s_setprio 0
	s_barrier
	s_add_u32 s18, s22, 0xb0080
	s_addc_u32 s19, s23, 0
	s_add_i32 s22, s24, s29
	s_mov_b32 m0, s22
	s_nop 0
	global_load_lds_dwordx4 v192, s[18:19]
	s_add_i32 m0, s22, 0x2000
	s_nop 0
	global_load_lds_dwordx4 v210, s[18:19]
	s_waitcnt vmcnt(6)
	s_barrier
	s_setprio 1
	v_mfma_f32_16x16x32_bf16 v[52:55], v[176:179], v[144:147], v[52:55]
	v_mfma_f32_16x16x32_bf16 v[48:51], v[184:187], v[144:147], v[48:51]
	v_mfma_f32_16x16x32_bf16 v[36:39], v[176:179], v[152:155], v[36:39]
	v_mfma_f32_16x16x32_bf16 v[32:35], v[184:187], v[152:155], v[32:35]
	v_mfma_f32_16x16x32_bf16 v[20:23], v[176:179], v[160:163], v[20:23]
	v_mfma_f32_16x16x32_bf16 v[16:19], v[184:187], v[160:163], v[16:19]
	v_mfma_f32_16x16x32_bf16 v[4:7], v[176:179], v[168:171], v[4:7]
	v_mfma_f32_16x16x32_bf16 v[0:3], v[184:187], v[168:171], v[0:3]
	v_mfma_f32_16x16x32_bf16 v[52:55], v[180:183], v[148:151], v[52:55]
	v_mfma_f32_16x16x32_bf16 v[48:51], v[188:191], v[148:151], v[48:51]
	v_mfma_f32_16x16x32_bf16 v[36:39], v[180:183], v[156:159], v[36:39]
	v_mfma_f32_16x16x32_bf16 v[32:35], v[188:191], v[156:159], v[32:35]
	v_mfma_f32_16x16x32_bf16 v[20:23], v[180:183], v[164:167], v[20:23]
	v_mfma_f32_16x16x32_bf16 v[16:19], v[188:191], v[164:167], v[16:19]
	v_mfma_f32_16x16x32_bf16 v[4:7], v[180:183], v[172:175], v[4:7]
	v_mfma_f32_16x16x32_bf16 v[0:3], v[188:191], v[172:175], v[0:3]
	s_setprio 0
	s_add_i32 s44, s44, 2
	s_add_u32 s33, s33, 0x100
	s_addc_u32 s43, s43, 0
	s_cmp_gt_u32 s44, 41
	s_mov_b64 s[18:19], s[20:21]
	s_barrier
	s_cbranch_scc0 .LBB0_3618
	v_mov_b32_e32 v128, v252
	s_lshl_b32 s19, s42, 8
	v_readfirstlane_b32 s18, v128
	s_ashr_i32 s20, s18, 2
	s_andn2_b32 s20, s20, 63
	s_lshr_b32 s18, s18, 1
	s_add_i32 s20, s20, s19
	s_and_b32 s18, s18, 0x60
	s_lshl_b32 s19, s41, 8
	v_and_or_b32 v218, v128, 15, s20
	v_lshrrev_b32_e32 v128, 1, v128
	s_or_b32 s18, s18, s19
	v_and_b32_e32 v129, 64, v195
	v_and_or_b32 v216, v128, 24, s18
	v_xor_b32_e32 v128, 16, v195
	v_add_u32_e32 v129, 64, v129
	v_cmp_lt_i32_e32 vcc, v128, v129
	v_ashrrev_i32_e32 v219, 31, v218
	v_ashrrev_i32_e32 v217, 31, v216
	v_cndmask_b32_e32 v128, v195, v128, vcc
	v_lshlrev_b32_e32 v200, 2, v128
	v_xor_b32_e32 v128, 32, v195
	v_cmp_lt_i32_e32 vcc, v128, v129
	v_or_b32_e32 v220, 0x80, v216
	v_ashrrev_i32_e32 v221, 31, v220
	v_cndmask_b32_e32 v128, v195, v128, vcc
	v_lshlrev_b32_e32 v199, 2, v128
	v_lshlrev_b64 v[128:129], 10, v[218:219]
	v_lshl_add_u64 v[130:131], v[128:129], 0, v[216:217]
	v_lshlrev_b64 v[130:131], 1, v[130:131]
	v_lshl_add_u64 v[246:247], s[10:11], 0, v[130:131]
	v_lshl_add_u64 v[250:251], s[12:13], 0, v[130:131]
	global_load_dwordx4 v[188:191], v[246:247], off
	global_load_dwordx4 v[180:183], v[246:247], off offset:256
	global_load_dwordx4 v[184:187], v[250:251], off
	v_or_b32_e32 v242, 16, v218
	v_lshl_add_u64 v[128:129], v[128:129], 0, v[220:221]
	v_ashrrev_i32_e32 v243, 31, v242
	v_lshl_add_u64 v[248:249], v[128:129], 1, s[12:13]
	v_lshlrev_b64 v[128:129], 10, v[242:243]
	v_or_b32_e32 v234, 32, v218
	v_lshl_add_u64 v[130:131], v[128:129], 0, v[216:217]
	v_lshl_add_u64 v[128:129], v[128:129], 0, v[220:221]
	v_ashrrev_i32_e32 v235, 31, v234
	v_lshlrev_b64 v[130:131], 1, v[130:131]
	v_lshl_add_u64 v[240:241], v[128:129], 1, s[12:13]
	v_lshlrev_b64 v[128:129], 10, v[234:235]
	v_or_b32_e32 v226, 48, v218
	v_lshl_add_u64 v[238:239], s[10:11], 0, v[130:131]
	v_lshl_add_u64 v[244:245], s[12:13], 0, v[130:131]
	v_lshl_add_u64 v[130:131], v[128:129], 0, v[216:217]
	v_lshl_add_u64 v[128:129], v[128:129], 0, v[220:221]
	v_ashrrev_i32_e32 v227, 31, v226
	v_lshlrev_b64 v[130:131], 1, v[130:131]
	v_lshl_add_u64 v[232:233], v[128:129], 1, s[12:13]
	v_lshlrev_b64 v[128:129], 10, v[226:227]
	v_lshl_add_u64 v[228:229], s[10:11], 0, v[130:131]
	v_lshl_add_u64 v[236:237], s[12:13], 0, v[130:131]
	v_lshl_add_u64 v[130:131], v[128:129], 0, v[216:217]
	v_lshlrev_b64 v[130:131], 1, v[130:131]
	v_lshl_add_u64 v[132:133], v[128:129], 0, v[220:221]
	v_lshl_add_u64 v[222:223], s[10:11], 0, v[130:131]
	v_lshl_add_u64 v[230:231], s[12:13], 0, v[130:131]
	v_lshl_add_u64 v[224:225], v[132:133], 1, s[12:13]
	global_load_dwordx4 v[176:179], v[248:249], off
	global_load_dwordx4 v[172:175], v[238:239], off
	global_load_dwordx4 v[164:167], v[238:239], off offset:256
	global_load_dwordx4 v[168:171], v[244:245], off
	global_load_dwordx4 v[160:163], v[240:241], off
	global_load_dwordx4 v[156:159], v[228:229], off
	global_load_dwordx4 v[132:135], v[224:225], off
	global_load_dwordx4 v[152:155], v[236:237], off
	global_load_dwordx4 v[144:147], v[232:233], off
	global_load_dwordx4 v[148:151], v[228:229], off offset:256
	global_load_dwordx4 v[136:139], v[230:231], off
	global_load_dwordx4 v[140:143], v[222:223], off
	global_load_dwordx4 v[128:131], v[222:223], off offset:256
	v_cmp_gt_u32_e32 vcc, 16, v195
	s_waitcnt vmcnt(0)
	v_lshlrev_b32_e32 v202, 16, v188
	v_and_b32_e32 v203, 0xffff0000, v188
	v_lshlrev_b32_e32 v204, 16, v184
	v_and_b32_e32 v205, 0xffff0000, v184
	v_lshlrev_b32_e32 v188, 16, v189
	v_and_b32_e32 v189, 0xffff0000, v189
	v_lshlrev_b32_e32 v184, 16, v185
	v_and_b32_e32 v185, 0xffff0000, v185
	v_pk_add_f32 v[202:203], v[202:203], v[204:205]
	v_pk_add_f32 v[184:185], v[188:189], v[184:185]
	v_pk_fma_f32 v[188:189], v[124:125], 0.5, v[202:203] op_sel_hi:[1,0,1]
	v_pk_fma_f32 v[184:185], v[126:127], 0.5, v[184:185] op_sel_hi:[1,0,1]
	v_lshlrev_b32_e32 v124, 16, v190
	v_and_b32_e32 v125, 0xffff0000, v190
	v_lshlrev_b32_e32 v126, 16, v186
	v_and_b32_e32 v127, 0xffff0000, v186
	v_pk_add_f32 v[124:125], v[124:125], v[126:127]
	v_lshlrev_b32_e32 v126, 16, v191
	v_and_b32_e32 v127, 0xffff0000, v191
	v_lshlrev_b32_e32 v186, 16, v187
	v_and_b32_e32 v187, 0xffff0000, v187
	v_pk_add_f32 v[126:127], v[126:127], v[186:187]
	v_pk_fma_f32 v[190:191], v[120:121], 0.5, v[124:125] op_sel_hi:[1,0,1]
	v_cvt_pk_bf16_f32 v120, v188, v189
	v_pk_fma_f32 v[186:187], v[122:123], 0.5, v[126:127] op_sel_hi:[1,0,1]
	v_and_b32_e32 v123, 0xffff0000, v120
	v_lshlrev_b32_e32 v122, 16, v120
	v_pk_add_f32 v[122:123], v[188:189], v[122:123] neg_lo:[0,1] neg_hi:[0,1]
	v_cvt_pk_bf16_f32 v121, v184, v185
	v_cvt_pk_bf16_f32 v124, v122, v123
	v_and_b32_e32 v123, 0xffff0000, v121
	v_lshlrev_b32_e32 v122, 16, v121
	v_pk_add_f32 v[122:123], v[184:185], v[122:123] neg_lo:[0,1] neg_hi:[0,1]
	s_nop 0
	v_cvt_pk_bf16_f32 v125, v122, v123
	v_cvt_pk_bf16_f32 v122, v190, v191
	v_cvt_pk_bf16_f32 v123, v186, v187
	v_and_b32_e32 v127, 0xffff0000, v122
	v_lshlrev_b32_e32 v126, 16, v122
	v_and_b32_e32 v203, 0xffff0000, v123
	v_lshlrev_b32_e32 v202, 16, v123
	v_pk_add_f32 v[126:127], v[190:191], v[126:127] neg_lo:[0,1] neg_hi:[0,1]
	v_pk_add_f32 v[202:203], v[186:187], v[202:203] neg_lo:[0,1] neg_hi:[0,1]
	v_cvt_pk_bf16_f32 v126, v126, v127
	v_cvt_pk_bf16_f32 v127, v202, v203
	global_store_dwordx4 v[246:247], v[120:123], off
	global_store_dwordx4 v[250:251], v[124:127], off
	s_nop 0
	v_pk_mul_f32 v[122:123], v[190:191], v[190:191]
	v_pk_mul_f32 v[120:121], v[186:187], v[186:187]
	v_pk_fma_f32 v[122:123], v[188:189], v[188:189], v[122:123]
	v_pk_fma_f32 v[120:121], v[184:185], v[184:185], v[120:121]
	v_add_f32_e32 v122, v122, v123
	v_add_f32_e32 v120, v120, v122
	v_add_f32_e32 v120, v121, v120
	ds_bpermute_b32 v121, v200, v120
	s_waitcnt lgkmcnt(0)
	v_add_f32_e32 v122, v120, v121
	ds_bpermute_b32 v123, v199, v122
	v_lshl_add_u64 v[120:121], v[218:219], 2, s[16:17]
	s_and_saveexec_b64 s[18:19], vcc
	s_cbranch_execz .LBB0_3621
	s_waitcnt lgkmcnt(0)
	v_add_f32_e32 v122, v122, v123
	global_atomic_add_f32 v[120:121], v122, off
